# diff attention: next-stage LDS-DMA pieces issued two at a time behind the first four MFMA groups instead of an 8-piece burst at the loop top; plus DPP wave sums, deferred bf16 unpack in E phases, max
# speedup vs baseline: 1.0190x; 1.0190x over previous
; #define GAS __attribute__((address_space(1)))
; DI unsigned pk2(float lo, float hi) { f32x2_t v = {lo, hi}; bf16x2_t b = __builtin_convertvector(v, bf16x2_t); return __builtin_bit_cast(unsigned, b); }
; DI float wave_sum(float v) {
; #pragma unroll
;     for (int o = 1; o < 64; o <<= 1) v += __shfl_xor(v, o);
;     return v;
; }
; DI void phase_e(const Ctx& C, int nslab, int has_post, int pl, int ps, float pw, int has_pre, int ql, int qs, int nrows,
;                 const GAS float* xsrc, const GAS float* csrc, GAS float* xdst, GAS float* cdst, bool xs16, bool xd16) {
;     ...
;         if (has_pre) {
;             float ss = 0.f;
; #pragma unroll
;             for (int j = 0; j < 4; ++j) ss += (v[j][0] * v[j][0] + v[j][1] * v[j][1]) + (v[j][2] * v[j][2] + v[j][3] * v[j][3]);
;             const float r = rsqrtf(wave_sum(ss) * (1.0f / 1024.0f) + EPS);
; #pragma unroll
;             for (int j = 0; j < 4; ++j) { const f32x4 h = ((v[j] * r) * gpr[j]) * (1.0f + sc[j]) + sh[j];
;                 u32x2 w; w.x = pk2(h[0], h[1]); w.y = pk2(h[2], h[3]); *(GAS u32x2*)(H + (size_t)row * 1024 + 256 * j + 4 * lane) = w; }
;         }
.LBB0_189:
	v_pk_mul_f32 v[110:111], v[48:49], v[48:49]
	v_pk_mul_f32 v[112:113], v[46:47], v[46:47]
	s_ashr_i32 s3, s2, 31
	v_pk_mov_b32 v[114:115], v[112:113], v[110:111] op_sel:[1,0]
	v_mov_b32_e32 v113, v111
	v_pk_add_f32 v[110:111], v[114:115], v[112:113]
	v_pk_mul_f32 v[112:113], v[28:29], v[28:29]
	v_pk_add_f32 v[110:111], v[110:111], v[110:111] op_sel_hi:[0,1]
	v_pk_mul_f32 v[114:115], v[26:27], v[26:27]
	v_mul_f32_e32 v110, v22, v22
	v_pk_mov_b32 v[116:117], v[114:115], v[112:113] op_sel:[1,0]
	v_mov_b32_e32 v115, v113
	v_pk_add_f32 v[112:113], v[116:117], v[114:115]
	v_pk_fma_f32 v[114:115], v[22:23], v[22:23], v[110:111] op_sel_hi:[1,1,0]
	v_mul_f32_e32 v110, v24, v24
	v_pk_add_f32 v[112:113], v[112:113], v[112:113] op_sel_hi:[0,1]
	v_pk_fma_f32 v[116:117], v[24:25], v[24:25], v[110:111] op_sel_hi:[1,1,0]
	v_mul_f32_e32 v114, v18, v18
	v_mul_f32_e32 v116, v19, v19
	v_mul_f32_e32 v112, v20, v20
	v_mul_f32_e32 v110, v21, v21
	v_pk_add_f32 v[114:115], v[114:115], v[116:117]
	v_pk_add_f32 v[110:111], v[112:113], v[110:111]
	s_lshl_b64 s[2:3], s[2:3], 11
	v_pk_add_f32 v[110:111], v[114:115], v[110:111]
	v_lshl_add_u64 v[114:115], v[100:101], 0, s[2:3]
	v_add_f32_e32 v109, v110, v111
	s_nop 1
	v_add_f32_dpp v109, v109, v109 quad_perm:[1,0,3,2] row_mask:0xf bank_mask:0xf
	s_nop 1
	v_add_f32_dpp v109, v109, v109 quad_perm:[2,3,0,1] row_mask:0xf bank_mask:0xf
	s_nop 1
	v_add_f32_dpp v109, v109, v109 row_half_mirror row_mask:0xf bank_mask:0xf
	s_nop 1
	v_add_f32_dpp v109, v109, v109 row_mirror row_mask:0xf bank_mask:0xf
	s_nop 0
	v_readlane_b32 s64, v109, 0
	v_readlane_b32 s65, v109, 16
	v_readlane_b32 s66, v109, 32
	v_readlane_b32 s67, v109, 48
	v_mov_b32_e32 v110, s65
	v_add_f32_e32 v110, s64, v110
	v_mov_b32_e32 v109, s67
	v_add_f32_e32 v109, s66, v109
	v_add_f32_e32 v109, v110, v109
	s_waitcnt lgkmcnt(0)
	s_add_i32 s6, s6, 8
	s_cmp_lt_i32 s6, s8
	s_waitcnt vmcnt(3)
	v_pk_add_f32 v[110:111], v[68:69], 1.0 op_sel_hi:[1,0]
	v_fmamk_f32 v109, v109, 0x3a800000, v108
	v_mul_f32_e32 v112, 0x4b800000, v109
	v_cmp_gt_f32_e32 vcc, s22, v109
	s_nop 1
	v_cndmask_b32_e32 v109, v109, v112, vcc
	v_rsq_f32_e32 v109, v109
	v_pk_add_f32 v[112:113], v[66:67], 1.0 op_sel_hi:[1,0]
	v_mul_f32_e32 v116, 0x45800000, v109
	v_cndmask_b32_e32 v116, v109, v116, vcc
	v_pk_mul_f32 v[48:49], v[48:49], v[116:117] op_sel_hi:[1,0]
	v_pk_mul_f32 v[46:47], v[46:47], v[116:117] op_sel_hi:[1,0]
	v_pk_mul_f32 v[48:49], v[4:5], v[48:49]
	v_pk_mul_f32 v[46:47], v[2:3], v[46:47]
	v_pk_fma_f32 v[48:49], v[110:111], v[48:49], v[64:65]
	v_pk_fma_f32 v[46:47], v[112:113], v[46:47], v[62:63]
	v_pk_mul_f32 v[28:29], v[28:29], v[116:117] op_sel_hi:[1,0]
	v_cvt_pk_bf16_f32 v46, v46, v47
	v_cvt_pk_bf16_f32 v47, v48, v49
	v_pk_mul_f32 v[26:27], v[26:27], v[116:117] op_sel_hi:[1,0]
	global_store_dwordx2 v[114:115], v[46:47], off
	v_pk_mul_f32 v[26:27], v[6:7], v[26:27]
	v_pk_mul_f32 v[28:29], v[8:9], v[28:29]
	v_pk_add_f32 v[46:47], v[60:61], 1.0 op_sel_hi:[1,0]
	v_pk_add_f32 v[48:49], v[58:59], 1.0 op_sel_hi:[1,0]
	v_pk_fma_f32 v[28:29], v[46:47], v[28:29], v[72:73]
	v_pk_fma_f32 v[26:27], v[48:49], v[26:27], v[70:71]
	v_pk_mul_f32 v[24:25], v[24:25], v[116:117] op_sel_hi:[1,0]
	v_cvt_pk_bf16_f32 v26, v26, v27
	v_cvt_pk_bf16_f32 v27, v28, v29
	v_pk_mul_f32 v[22:23], v[22:23], v[116:117] op_sel_hi:[1,0]
	global_store_dwordx2 v[114:115], v[26:27], off offset:512
	v_pk_mul_f32 v[22:23], v[10:11], v[22:23]
	v_pk_mul_f32 v[24:25], v[12:13], v[24:25]
	v_pk_add_f32 v[26:27], v[56:57], 1.0 op_sel_hi:[1,0]
	v_pk_add_f32 v[28:29], v[54:55], 1.0 op_sel_hi:[1,0]
	s_waitcnt vmcnt(3)
	v_pk_fma_f32 v[24:25], v[26:27], v[24:25], v[80:81]
	v_pk_fma_f32 v[22:23], v[28:29], v[22:23], v[78:79]
	v_pk_mul_f32 v[20:21], v[20:21], v[116:117] op_sel_hi:[1,0]
	v_cvt_pk_bf16_f32 v22, v22, v23
	v_cvt_pk_bf16_f32 v23, v24, v25
	v_pk_mul_f32 v[18:19], v[18:19], v[116:117] op_sel_hi:[1,0]
	global_store_dwordx2 v[114:115], v[22:23], off offset:1024
	v_pk_mul_f32 v[18:19], v[14:15], v[18:19]
	v_pk_mul_f32 v[20:21], v[16:17], v[20:21]
	v_pk_add_f32 v[22:23], v[52:53], 1.0 op_sel_hi:[1,0]
	v_pk_add_f32 v[24:25], v[50:51], 1.0 op_sel_hi:[1,0]
	s_waitcnt vmcnt(3)
	v_pk_fma_f32 v[20:21], v[22:23], v[20:21], v[76:77]
	v_pk_fma_f32 v[18:19], v[24:25], v[18:19], v[74:75]
	v_mov_b64_e32 v[22:23], v[38:39]
	v_cvt_pk_bf16_f32 v18, v18, v19
	v_cvt_pk_bf16_f32 v19, v20, v21
	global_store_dwordx2 v[114:115], v[18:19], off offset:1536
	v_mov_b64_e32 v[18:19], v[42:43]
	v_mov_b64_e32 v[26:27], v[34:35]
	v_mov_b64_e32 v[48:49], v[32:33]
	v_mov_b64_e32 v[20:21], v[44:45]
	v_mov_b64_e32 v[24:25], v[40:41]
	v_mov_b64_e32 v[28:29], v[36:37]
	v_mov_b64_e32 v[46:47], v[30:31]
	v_mov_b64_e32 v[42:43], v[82:83]
	v_mov_b64_e32 v[38:39], v[86:87]
	v_mov_b64_e32 v[34:35], v[90:91]
	v_mov_b64_e32 v[30:31], v[94:95]
	v_mov_b64_e32 v[44:45], v[84:85]
	v_mov_b64_e32 v[40:41], v[88:89]
	v_mov_b64_e32 v[36:37], v[92:93]
	v_mov_b64_e32 v[32:33], v[96:97]
	s_cbranch_scc0 .LBB0_194

; #define GAS __attribute__((address_space(1)))
; DI unsigned pk2(float lo, float hi) { f32x2_t v = {lo, hi}; bf16x2_t b = __builtin_convertvector(v, bf16x2_t); return __builtin_bit_cast(unsigned, b); }
; DI float wave_sum(float v) {
; #pragma unroll
;     for (int o = 1; o < 64; o <<= 1) v += __shfl_xor(v, o);
;     return v;
; }
; DI void phase_e(const Ctx& C, int nslab, int has_post, int pl, int ps, float pw, int has_pre, int ql, int qs, int nrows,
;                 const GAS float* xsrc, const GAS float* csrc, GAS float* xdst, GAS float* cdst, bool xs16, bool xd16) {
;     ...
;         if (has_pre) {
;             float ss = 0.f;
; #pragma unroll
;             for (int j = 0; j < 4; ++j) ss += (v[j][0] * v[j][0] + v[j][1] * v[j][1]) + (v[j][2] * v[j][2] + v[j][3] * v[j][3]);
;             const float r = rsqrtf(wave_sum(ss) * (1.0f / 1024.0f) + EPS);
; #pragma unroll
;             for (int j = 0; j < 4; ++j) { const f32x4 h = ((v[j] * r) * gpr[j]) * (1.0f + sc[j]) + sh[j];
;                 u32x2 w; w.x = pk2(h[0], h[1]); w.y = pk2(h[2], h[3]); *(GAS u32x2*)(H + (size_t)row * 1024 + 256 * j + 4 * lane) = w; }
;         }
.LBB0_424:
	v_pk_mul_f32 v[54:55], v[128:129], v[128:129]
	v_pk_mul_f32 v[56:57], v[126:127], v[126:127]
	v_pk_mul_f32 v[50:51], v[132:133], v[132:133]
	v_pk_mul_f32 v[52:53], v[130:131], v[130:131]
	v_pk_mov_b32 v[58:59], v[56:57], v[54:55] op_sel:[1,0]
	v_mov_b32_e32 v57, v55
	v_pk_add_f32 v[54:55], v[58:59], v[56:57]
	v_pk_mov_b32 v[56:57], v[52:53], v[50:51] op_sel:[1,0]
	v_mov_b32_e32 v53, v51
	v_pk_add_f32 v[50:51], v[56:57], v[52:53]
	v_pk_add_f32 v[54:55], v[54:55], v[54:55] op_sel_hi:[0,1]
	v_pk_add_f32 v[50:51], v[50:51], v[50:51] op_sel_hi:[0,1]
	v_mul_f32_e32 v50, v134, v134
	v_pk_fma_f32 v[52:53], v[134:135], v[134:135], v[50:51] op_sel_hi:[1,1,0]
	v_mul_f32_e32 v50, v136, v136
	v_pk_fma_f32 v[56:57], v[136:137], v[136:137], v[50:51] op_sel_hi:[1,1,0]
	v_mul_f32_e32 v52, v138, v138
	v_mul_f32_e32 v56, v139, v139
	v_mul_f32_e32 v54, v140, v140
	v_mul_f32_e32 v50, v141, v141
	v_pk_add_f32 v[52:53], v[52:53], v[56:57]
	v_pk_add_f32 v[50:51], v[54:55], v[50:51]
	v_pk_add_f32 v[54:55], v[66:67], 1.0 op_sel_hi:[1,0]
	v_pk_add_f32 v[50:51], v[52:53], v[50:51]
	v_pk_add_f32 v[52:53], v[68:69], 1.0 op_sel_hi:[1,0]
	v_add_f32_e32 v50, v50, v51
	s_nop 1
	v_add_f32_dpp v50, v50, v50 quad_perm:[1,0,3,2] row_mask:0xf bank_mask:0xf
	s_nop 1
	v_add_f32_dpp v50, v50, v50 quad_perm:[2,3,0,1] row_mask:0xf bank_mask:0xf
	s_nop 1
	v_add_f32_dpp v50, v50, v50 row_half_mirror row_mask:0xf bank_mask:0xf
	s_nop 1
	v_add_f32_dpp v50, v50, v50 row_mirror row_mask:0xf bank_mask:0xf
	s_nop 0
	v_readlane_b32 s64, v50, 0
	v_readlane_b32 s65, v50, 16
	v_readlane_b32 s66, v50, 32
	v_readlane_b32 s67, v50, 48
	v_mov_b32_e32 v51, s65
	v_add_f32_e32 v51, s64, v51
	v_mov_b32_e32 v50, s67
	v_add_f32_e32 v50, s66, v50
	v_add_f32_e32 v50, v51, v50
	s_waitcnt lgkmcnt(0)
	s_add_i32 s0, s43, 8
	s_add_i32 s1, s43, -8
	s_cmp_lt_i32 s1, s27
	s_mov_b32 s43, s0
	v_mov_b64_e32 v[170:171], v[144:145]
	s_waitcnt vmcnt(3)
	v_mov_b64_e32 v[144:145], v[162:163]
	v_fmamk_f32 v50, v50, 0x3a800000, v197
	v_mul_f32_e32 v51, 0x4b800000, v50
	v_cmp_gt_f32_e32 vcc, s47, v50
	s_nop 1
	v_cndmask_b32_e32 v50, v50, v51, vcc
	v_rsq_f32_e32 v56, v50
	v_lshl_add_u64 v[50:51], v[158:159], 0, s[2:3]
	v_mul_f32_e32 v57, 0x45800000, v56
	v_cndmask_b32_e32 v56, v56, v57, vcc
	v_pk_mul_f32 v[58:59], v[128:129], v[56:57] op_sel_hi:[1,0]
	v_pk_mul_f32 v[60:61], v[126:127], v[56:57] op_sel_hi:[1,0]
	v_pk_mul_f32 v[58:59], v[12:13], v[58:59]
	v_pk_mul_f32 v[60:61], v[10:11], v[60:61]
	v_pk_fma_f32 v[52:53], v[52:53], v[58:59], v[72:73]
	v_pk_fma_f32 v[54:55], v[54:55], v[60:61], v[70:71]
	v_pk_mul_f32 v[126:127], v[132:133], v[56:57] op_sel_hi:[1,0]
	v_pk_mul_f32 v[128:129], v[130:131], v[56:57] op_sel_hi:[1,0]
	v_cvt_pk_bf16_f32 v54, v54, v55
	v_cvt_pk_bf16_f32 v55, v52, v53
	v_pk_mul_f32 v[128:129], v[14:15], v[128:129]
	global_store_dwordx2 v[50:51], v[54:55], off
	v_pk_mul_f32 v[52:53], v[16:17], v[126:127]
	v_pk_add_f32 v[54:55], v[76:77], 1.0 op_sel_hi:[1,0]
	v_pk_add_f32 v[58:59], v[74:75], 1.0 op_sel_hi:[1,0]
	v_pk_fma_f32 v[52:53], v[54:55], v[52:53], v[80:81]
	v_pk_fma_f32 v[54:55], v[58:59], v[128:129], v[78:79]
	v_pk_add_f32 v[58:59], v[84:85], 1.0 op_sel_hi:[1,0]
	v_cvt_pk_bf16_f32 v54, v54, v55
	v_cvt_pk_bf16_f32 v55, v52, v53
	global_store_dwordx2 v[50:51], v[54:55], off offset:512
	v_pk_mul_f32 v[52:53], v[136:137], v[56:57] op_sel_hi:[1,0]
	v_pk_mul_f32 v[54:55], v[134:135], v[56:57] op_sel_hi:[1,0]
	v_pk_mul_f32 v[52:53], v[28:29], v[52:53]
	v_pk_mul_f32 v[54:55], v[26:27], v[54:55]
	v_pk_add_f32 v[60:61], v[82:83], 1.0 op_sel_hi:[1,0]
	s_waitcnt vmcnt(3)
	v_pk_fma_f32 v[52:53], v[58:59], v[52:53], v[92:93]
	v_pk_fma_f32 v[54:55], v[60:61], v[54:55], v[90:91]
	v_pk_add_f32 v[58:59], v[62:63], 1.0 op_sel_hi:[1,0]
	v_cvt_pk_bf16_f32 v54, v54, v55
	v_cvt_pk_bf16_f32 v55, v52, v53
	global_store_dwordx2 v[50:51], v[54:55], off offset:1024
	v_pk_mul_f32 v[52:53], v[140:141], v[56:57] op_sel_hi:[1,0]
	v_pk_mul_f32 v[54:55], v[138:139], v[56:57] op_sel_hi:[1,0]
	v_pk_mul_f32 v[52:53], v[32:33], v[52:53]
	v_pk_mul_f32 v[54:55], v[30:31], v[54:55]
	v_pk_add_f32 v[56:57], v[64:65], 1.0 op_sel_hi:[1,0]
	s_waitcnt vmcnt(3)
	v_pk_fma_f32 v[54:55], v[58:59], v[54:55], v[86:87]
	v_pk_fma_f32 v[52:53], v[56:57], v[52:53], v[88:89]
	v_cvt_pk_bf16_f32 v54, v54, v55
	v_cvt_pk_bf16_f32 v55, v52, v53
	global_store_dwordx2 v[50:51], v[54:55], off offset:1536
	v_mov_b64_e32 v[52:53], v[48:49]
	v_mov_b64_e32 v[56:57], v[44:45]
	v_mov_b64_e32 v[60:61], v[40:41]
	v_mov_b64_e32 v[128:129], v[36:37]
	v_mov_b64_e32 v[50:51], v[46:47]
	v_mov_b64_e32 v[54:55], v[42:43]
	v_mov_b64_e32 v[58:59], v[38:39]
	v_mov_b64_e32 v[126:127], v[34:35]
	v_mov_b64_e32 v[46:47], v[110:111]
	v_mov_b64_e32 v[42:43], v[114:115]
	v_mov_b64_e32 v[38:39], v[118:119]
	v_mov_b64_e32 v[34:35], v[122:123]
	v_mov_b64_e32 v[48:49], v[112:113]
	v_mov_b64_e32 v[44:45], v[116:117]
	v_mov_b64_e32 v[40:41], v[120:121]
	v_mov_b64_e32 v[36:37], v[124:125]
	v_mov_b64_e32 v[130:131], v[150:151]
	v_mov_b64_e32 v[132:133], v[148:149]
	v_mov_b64_e32 v[134:135], v[146:147]
	v_mov_b64_e32 v[150:151], v[168:169]
	v_mov_b64_e32 v[148:149], v[166:167]
	v_mov_b64_e32 v[146:147], v[164:165]
	s_cbranch_scc0 .LBB0_450

; #define GAS __attribute__((address_space(1)))
; DI unsigned pk2(float lo, float hi) { f32x2_t v = {lo, hi}; bf16x2_t b = __builtin_convertvector(v, bf16x2_t); return __builtin_bit_cast(unsigned, b); }
; DI float bflo(unsigned w) { return __uint_as_float(w << 16); }
; DI float bfhi(unsigned w) { return __uint_as_float(w & 0xffff0000u); }
; DI float wave_sum(float v) {
; #pragma unroll
;     for (int o = 1; o < 64; o <<= 1) v += __shfl_xor(v, o);
;     return v;
; }
; DI void phase_e(const Ctx& C, int nslab, int has_post, int pl, int ps, float pw, int has_pre, int ql, int qs, int nrows,
;                 const GAS float* xsrc, const GAS float* csrc, GAS float* xdst, GAS float* cdst, bool xs16, bool xd16) {
;     ...
;         if (has_post) {
;             f32x4 y[4]; float ss = 0.f;
; #pragma unroll
;             for (int j = 0; j < 4; ++j) {
;                 if (isx || nslab == 0) { y[j] = (f32x4){bflo(yw[j].x), bfhi(yw[j].x), bflo(yw[j].y), bfhi(yw[j].y)}; }
;                 else { y[j] = (f32x4){0.f, 0.f, 0.f, 0.f};
;                     for (int s = 0; s < nslab; ++s) { const u32x2 w = *(const GAS u32x2*)(YS + ((size_t)s * MC + (row - MX)) * 1024 + 256 * j + 4 * lane); y[j] += (f32x4){bflo(w.x), bfhi(w.x), bflo(w.y), bfhi(w.y)}; } }
;                 ss += (y[j][0] * y[j][0] + y[j][1] * y[j][1]) + (y[j][2] * y[j][2] + y[j][3] * y[j][3]); }
;             const float r = rsqrtf(wave_sum(ss) * (1.0f / 1024.0f) + EPS);
;             if (isx && xd16) { GAS bf16* d16 = (GAS bf16*)xdst + (size_t)row * 1024;
; #pragma unroll
;                 for (int j = 0; j < 4; ++j) { v[j] += pw * gt[j] * ((y[j] * r) * gpo[j]); u32x2 w; w.x = pk2(v[j][0], v[j][1]); w.y = pk2(v[j][2], v[j][3]); __builtin_nontemporal_store(w, (GAS u32x2*)(d16 + 256 * j + 4 * lane));
;                     v[j] = (f32x4){bflo(w.x), bfhi(w.x), bflo(w.y), bfhi(w.y)}; }
;             } else { GAS float* dst = isx ? xdst + (size_t)row * 1024 : cdst + (size_t)(row - MX) * 1024;
; #pragma unroll
;                 for (int j = 0; j < 4; ++j) { v[j] += pw * gt[j] * ((y[j] * r) * gpo[j]); __builtin_nontemporal_store(v[j], (GAS f32x4*)(dst + 256 * j + 4 * lane)); } }
.LBB0_446:
	v_mul_f32_e32 v130, v141, v141
	v_mul_f32_e32 v131, v139, v139
	v_fmac_f32_e32 v130, v140, v140
	v_fmac_f32_e32 v131, v138, v138
	v_add_f32_e32 v130, v130, v131
	v_mul_f32_e32 v131, v171, v171
	v_mul_f32_e32 v132, v173, v173
	v_fmac_f32_e32 v131, v170, v170
	v_fmac_f32_e32 v132, v172, v172
	v_add_f32_e32 v131, v131, v132
	v_add_f32_e32 v130, v130, v131
	v_mul_f32_e32 v131, v175, v175
	v_mul_f32_e32 v132, v177, v177
	v_fmac_f32_e32 v131, v174, v174
	v_fmac_f32_e32 v132, v176, v176
	v_add_f32_e32 v131, v131, v132
	v_add_f32_e32 v136, v130, v131
	v_pk_mul_f32 v[130:131], v[180:181], v[180:181]
	v_pk_mul_f32 v[132:133], v[178:179], v[178:179]
	s_and_b64 s[0:1], exec, s[0:1]
	v_pk_mov_b32 v[134:135], v[132:133], v[130:131] op_sel:[1,0]
	v_mov_b32_e32 v133, v131
	v_pk_add_f32 v[130:131], v[134:135], v[132:133]
	s_ashr_i32 s13, s12, 31
	v_add_f32_e32 v130, v130, v131
	v_add_f32_e32 v130, v136, v130
	s_nop 1
	v_add_f32_dpp v130, v130, v130 quad_perm:[1,0,3,2] row_mask:0xf bank_mask:0xf
	s_nop 1
	v_add_f32_dpp v130, v130, v130 quad_perm:[2,3,0,1] row_mask:0xf bank_mask:0xf
	s_nop 1
	v_add_f32_dpp v130, v130, v130 row_half_mirror row_mask:0xf bank_mask:0xf
	s_nop 1
	v_add_f32_dpp v130, v130, v130 row_mirror row_mask:0xf bank_mask:0xf
	s_nop 0
	v_readlane_b32 s64, v130, 0
	v_readlane_b32 s65, v130, 16
	v_readlane_b32 s66, v130, 32
	v_readlane_b32 s67, v130, 48
	v_mov_b32_e32 v131, s65
	v_add_f32_e32 v131, s64, v131
	v_mov_b32_e32 v130, s67
	v_add_f32_e32 v130, s66, v130
	v_add_f32_e32 v132, v131, v130
	s_waitcnt lgkmcnt(0)
	s_mov_b64 s[22:23], -1
	s_waitcnt vmcnt(7)
	v_pk_mul_f32 v[188:189], v[98:99], 0.5 op_sel_hi:[1,0]
	s_waitcnt vmcnt(6)
	v_pk_mul_f32 v[186:187], v[102:103], 0.5 op_sel_hi:[1,0]
	s_waitcnt vmcnt(4)
	v_pk_mul_f32 v[184:185], v[106:107], 0.5 op_sel_hi:[1,0]
	v_pk_mul_f32 v[130:131], v[96:97], 0.5 op_sel_hi:[1,0]
	v_fmamk_f32 v132, v132, 0x3a800000, v197
	v_mul_f32_e32 v133, 0x4b800000, v132
	v_cmp_gt_f32_e32 vcc, s47, v132
	s_nop 1
	v_cndmask_b32_e32 v132, v132, v133, vcc
	v_rsq_f32_e32 v134, v132
	v_pk_mul_f32 v[132:133], v[94:95], 0.5 op_sel_hi:[1,0]
	v_mul_f32_e32 v135, 0x45800000, v134
	v_cndmask_b32_e32 v182, v134, v135, vcc
	v_mov_b32_e32 v183, v182
	v_pk_mul_f32 v[134:135], v[138:139], v[182:183] op_sel_hi:[1,0]
	v_pk_mul_f32 v[136:137], v[140:141], v[182:183] op_sel_hi:[1,0]
	v_pk_mul_f32 v[134:135], v[4:5], v[134:135]
	v_pk_mul_f32 v[136:137], v[2:3], v[136:137]
	v_pk_fma_f32 v[128:129], v[130:131], v[134:135], v[128:129]
	v_pk_fma_f32 v[126:127], v[132:133], v[136:137], v[126:127]
	s_mov_b64 vcc, s[0:1]
	s_cbranch_vccz .LBB0_448
	v_mov_b32_e32 v138, v182
	v_mov_b32_e32 v139, v182
	v_pk_mul_f32 v[132:133], v[172:173], v[138:139]
	v_pk_mul_f32 v[134:135], v[170:171], v[182:183]
	v_pk_mul_f32 v[130:131], v[100:101], 0.5 op_sel_hi:[1,0]
	v_pk_mul_f32 v[132:133], v[8:9], v[132:133]
	v_pk_mul_f32 v[134:135], v[6:7], v[134:135]
	v_pk_mul_f32 v[136:137], v[176:177], v[138:139]
	v_pk_mul_f32 v[140:141], v[174:175], v[182:183]
	v_pk_fma_f32 v[132:133], v[130:131], v[132:133], v[60:61]
	v_pk_fma_f32 v[130:131], v[188:189], v[134:135], v[58:59]
	v_pk_mul_f32 v[134:135], v[104:105], 0.5 op_sel_hi:[1,0]
	v_pk_mul_f32 v[136:137], v[20:21], v[136:137]
	v_pk_mul_f32 v[140:141], v[18:19], v[140:141]
	v_pk_mul_f32 v[138:139], v[180:181], v[138:139]
	v_pk_mul_f32 v[200:201], v[178:179], v[182:183]
	s_lshl_b64 s[0:1], s[6:7], 12
	v_pk_fma_f32 v[136:137], v[134:135], v[136:137], v[56:57]
	v_pk_fma_f32 v[134:135], v[186:187], v[140:141], v[54:55]
	v_pk_mul_f32 v[140:141], v[108:109], 0.5 op_sel_hi:[1,0]
	v_pk_mul_f32 v[138:139], v[24:25], v[138:139]
	v_pk_mul_f32 v[200:201], v[22:23], v[200:201]
	v_lshl_add_u64 v[198:199], v[160:161], 0, s[0:1]
	v_pk_fma_f32 v[140:141], v[140:141], v[138:139], v[52:53]
	v_pk_fma_f32 v[138:139], v[184:185], v[200:201], v[50:51]
	global_store_dwordx4 v[198:199], v[126:129], off nt
	global_store_dwordx4 v[198:199], v[130:133], off offset:1024 nt
	global_store_dwordx4 v[198:199], v[134:137], off offset:2048 nt
	global_store_dwordx4 v[198:199], v[138:141], off offset:3072 nt
	s_lshl_b64 s[2:3], s[12:13], 11
	s_mov_b64 s[22:23], 0

; #define GAS __attribute__((address_space(1)))
; DI unsigned pk2(float lo, float hi) { f32x2_t v = {lo, hi}; bf16x2_t b = __builtin_convertvector(v, bf16x2_t); return __builtin_bit_cast(unsigned, b); }
; DI float silu(float x) { return x * sigm(x); }
; DI float wave_sum(float v) {
; #pragma unroll
;     for (int o = 1; o < 64; o <<= 1) v += __shfl_xor(v, o);
;     return v;
; }
; DI void phase_conv(const Ctx& C) {
;     ...
;         const float mean = wave_sum((a0[0] + a0[1]) + (a0[2] + a0[3]) + (a1[0] + a1[1]) + (a1[2] + a1[3])) * (1.0f / 512.0f);
;         a0 -= mean; a1 -= mean;
;         const float var = wave_sum((a0[0] * a0[0] + a0[1] * a0[1]) + (a0[2] * a0[2] + a0[3] * a0[3]) + (a1[0] * a1[0] + a1[1] * a1[1]) + (a1[2] * a1[2] + a1[3] * a1[3])) * (1.0f / 512.0f);
;         const float r = rsqrtf(var + EPS);
;         a0 = a0 * r * lg0 + lb0; a1 = a1 * r * lg1 + lb1;
;         u32x4 o; o.x = pk2(silu(a0[0]), silu(a0[1])); o.y = pk2(silu(a0[2]), silu(a0[3])); o.z = pk2(silu(a1[0]), silu(a1[1])); o.w = pk2(silu(a1[2]), silu(a1[3]));
;         *(GAS u32x4*)(MIX + (size_t)row * 1024 + 512 + c0) = o;
.LBB0_615:
	v_mov_b32_e32 v26, v41
	v_mov_b32_e32 v27, v38
	v_mov_b32_e32 v28, v40
	v_mov_b32_e32 v29, v39
	v_pk_add_f32 v[26:27], v[26:27], v[28:29]
	v_mov_b32_e32 v28, v42
	v_mov_b32_e32 v29, v44
	v_mov_b32_e32 v30, v43
	v_mov_b32_e32 v31, v45
	v_pk_add_f32 v[28:29], v[28:29], v[30:31]
	v_add_f32_e32 v26, v26, v27
	v_add_f32_e32 v26, v29, v26
	v_add_f32_e32 v26, v28, v26
	s_nop 1
	v_add_f32_dpp v26, v26, v26 quad_perm:[1,0,3,2] row_mask:0xf bank_mask:0xf
	s_nop 1
	v_add_f32_dpp v26, v26, v26 quad_perm:[2,3,0,1] row_mask:0xf bank_mask:0xf
	s_nop 1
	v_add_f32_dpp v26, v26, v26 row_half_mirror row_mask:0xf bank_mask:0xf
	s_nop 1
	v_add_f32_dpp v26, v26, v26 row_mirror row_mask:0xf bank_mask:0xf
	s_nop 0
	v_readlane_b32 s64, v26, 0
	v_readlane_b32 s65, v26, 16
	v_readlane_b32 s66, v26, 32
	v_readlane_b32 s67, v26, 48
	v_mov_b32_e32 v27, s65
	v_add_f32_e32 v27, s64, v27
	v_mov_b32_e32 v26, s67
	v_add_f32_e32 v26, s66, v26
	v_add_f32_e32 v26, v27, v26
	s_waitcnt lgkmcnt(0)
	s_ashr_i32 s3, s2, 31
	s_lshl_b64 s[0:1], s[2:3], 11
	s_add_i32 s2, s2, 8
	s_cmp_ge_i32 s2, s4
	v_fmamk_f32 v41, v26, 0xbb000000, v41
	v_fmac_f32_e32 v40, 0xbb000000, v26
	v_fmamk_f32 v39, v26, 0xbb000000, v39
	v_fmac_f32_e32 v38, 0xbb000000, v26
	v_fmamk_f32 v45, v26, 0xbb000000, v45
	v_fmac_f32_e32 v44, 0xbb000000, v26
	v_fmamk_f32 v43, v26, 0xbb000000, v43
	v_fmac_f32_e32 v42, 0xbb000000, v26
	v_pk_mul_f32 v[26:27], v[38:39], v[38:39]
	v_pk_mul_f32 v[28:29], v[40:41], v[40:41]
	v_pk_mul_f32 v[30:31], v[42:43], v[42:43]
	v_pk_mul_f32 v[32:33], v[44:45], v[44:45]
	v_pk_mov_b32 v[54:55], v[28:29], v[26:27] op_sel:[1,0]
	v_mov_b32_e32 v29, v27
	v_mov_b32_e32 v26, v30
	v_mov_b32_e32 v27, v32
	v_mov_b32_e32 v32, v31
	v_pk_add_f32 v[28:29], v[54:55], v[28:29]
	v_pk_add_f32 v[26:27], v[26:27], v[32:33]
	v_add_f32_e32 v28, v28, v29
	v_add_f32_e32 v27, v27, v28
	v_add_f32_e32 v26, v26, v27
	s_nop 1
	v_add_f32_dpp v26, v26, v26 quad_perm:[1,0,3,2] row_mask:0xf bank_mask:0xf
	s_nop 1
	v_add_f32_dpp v26, v26, v26 quad_perm:[2,3,0,1] row_mask:0xf bank_mask:0xf
	s_nop 1
	v_add_f32_dpp v26, v26, v26 row_half_mirror row_mask:0xf bank_mask:0xf
	s_nop 1
	v_add_f32_dpp v26, v26, v26 row_mirror row_mask:0xf bank_mask:0xf
	s_nop 0
	v_readlane_b32 s64, v26, 0
	v_readlane_b32 s65, v26, 16
	v_readlane_b32 s66, v26, 32
	v_readlane_b32 s67, v26, 48
	v_mov_b32_e32 v27, s65
	v_add_f32_e32 v27, s64, v27
	v_mov_b32_e32 v26, s67
	v_add_f32_e32 v26, s66, v26
	v_add_f32_e32 v26, v27, v26
	s_waitcnt lgkmcnt(0)
	v_fmamk_f32 v26, v26, 0x3b000000, v53
	v_mul_f32_e32 v27, 0x4b800000, v26
	v_cmp_gt_f32_e32 vcc, s8, v26
	s_nop 1
	v_cndmask_b32_e32 v26, v26, v27, vcc
	v_rsq_f32_e32 v26, v26
	s_nop 0
	v_mul_f32_e32 v27, 0x45800000, v26
	v_cndmask_b32_e32 v26, v26, v27, vcc
	v_pk_mul_f32 v[28:29], v[40:41], v[26:27] op_sel_hi:[1,0]
	v_pk_mul_f32 v[30:31], v[38:39], v[26:27] op_sel_hi:[1,0]
	v_pk_mul_f32 v[32:33], v[44:45], v[26:27] op_sel_hi:[1,0]
	v_pk_mul_f32 v[26:27], v[42:43], v[26:27] op_sel_hi:[1,0]
	v_pk_fma_f32 v[28:29], v[6:7], v[28:29], v[22:23]
	v_pk_fma_f32 v[38:39], v[12:13], v[26:27], v[16:17]
	v_mul_f32_e32 v26, 0xbfb8aa3b, v28
	v_mul_f32_e32 v27, 0xbfb8aa3b, v29
	v_exp_f32_e32 v26, v26
	v_exp_f32_e32 v27, v27
	v_pk_fma_f32 v[30:31], v[8:9], v[30:31], v[24:25]
	v_pk_fma_f32 v[32:33], v[10:11], v[32:33], v[14:15]
	v_mul_f32_e32 v40, 0xbfb8aa3b, v30
	v_mul_f32_e32 v41, 0xbfb8aa3b, v31
	v_add_f32_e32 v26, 1.0, v26
	v_add_f32_e32 v27, 1.0, v27
	v_mul_f32_e32 v42, 0xbfb8aa3b, v32
	v_mul_f32_e32 v43, 0xbfb8aa3b, v33
	v_mul_f32_e32 v44, 0xbfb8aa3b, v38
	v_mul_f32_e32 v45, 0xbfb8aa3b, v39
	v_exp_f32_e32 v40, v40
	v_exp_f32_e32 v41, v41
	v_rcp_f32_e32 v26, v26
	v_rcp_f32_e32 v27, v27
	v_exp_f32_e32 v42, v42
	v_exp_f32_e32 v43, v43
	v_exp_f32_e32 v44, v44
	v_exp_f32_e32 v45, v45
	v_add_f32_e32 v40, 1.0, v40
	v_add_f32_e32 v41, 1.0, v41
	v_pk_mul_f32 v[26:27], v[28:29], v[26:27]
	v_add_f32_e32 v42, 1.0, v42
	v_add_f32_e32 v43, 1.0, v43
	v_add_f32_e32 v44, 1.0, v44
	v_rcp_f32_e32 v40, v40
	v_rcp_f32_e32 v41, v41
	v_cvt_pk_bf16_f32 v26, v26, v27
	v_add_f32_e32 v27, 1.0, v45
	v_rcp_f32_e32 v42, v42
	v_rcp_f32_e32 v43, v43
	v_rcp_f32_e32 v44, v44
	v_rcp_f32_e32 v45, v27
	v_pk_mul_f32 v[28:29], v[30:31], v[40:41]
	v_pk_mul_f32 v[30:31], v[38:39], v[44:45]
	v_cvt_pk_bf16_f32 v27, v28, v29
	v_pk_mul_f32 v[28:29], v[32:33], v[42:43]
	s_nop 0
	v_cvt_pk_bf16_f32 v28, v28, v29
	v_cvt_pk_bf16_f32 v29, v30, v31
	v_lshl_add_u64 v[30:31], v[36:37], 0, s[0:1]
	global_store_dwordx4 v[30:31], v[26:29], off offset:1024
	s_cbranch_scc1 .LBB0_620

; #define GAS __attribute__((address_space(1)))
; DI unsigned pk2(float lo, float hi) { f32x2_t v = {lo, hi}; bf16x2_t b = __builtin_convertvector(v, bf16x2_t); return __builtin_bit_cast(unsigned, b); }
; DI float wave_sum(float v) {
; #pragma unroll
;     for (int o = 1; o < 64; o <<= 1) v += __shfl_xor(v, o);
;     return v;
; }
; DI void phase_e(const Ctx& C, int nslab, int has_post, int pl, int ps, float pw, int has_pre, int ql, int qs, int nrows,
;                 const GAS float* xsrc, const GAS float* csrc, GAS float* xdst, GAS float* cdst, bool xs16, bool xd16) {
;     ...
;         if (has_pre) {
;             float ss = 0.f;
; #pragma unroll
;             for (int j = 0; j < 4; ++j) ss += (v[j][0] * v[j][0] + v[j][1] * v[j][1]) + (v[j][2] * v[j][2] + v[j][3] * v[j][3]);
;             const float r = rsqrtf(wave_sum(ss) * (1.0f / 1024.0f) + EPS);
; #pragma unroll
;             for (int j = 0; j < 4; ++j) { const f32x4 h = ((v[j] * r) * gpr[j]) * (1.0f + sc[j]) + sh[j];
;                 u32x2 w; w.x = pk2(h[0], h[1]); w.y = pk2(h[2], h[3]); *(GAS u32x2*)(H + (size_t)row * 1024 + 256 * j + 4 * lane) = w; }
;         }
.LBB0_945:
	v_pk_mul_f32 v[54:55], v[80:81], v[80:81]
	v_pk_mul_f32 v[56:57], v[78:79], v[78:79]
	v_pk_mul_f32 v[46:47], v[132:133], v[132:133]
	v_pk_mul_f32 v[48:49], v[130:131], v[130:131]
	v_pk_mov_b32 v[58:59], v[56:57], v[54:55] op_sel:[1,0]
	v_mov_b32_e32 v57, v55
	v_pk_add_f32 v[54:55], v[58:59], v[56:57]
	v_pk_mov_b32 v[56:57], v[48:49], v[46:47] op_sel:[1,0]
	v_mov_b32_e32 v49, v47
	v_pk_add_f32 v[46:47], v[56:57], v[48:49]
	v_pk_add_f32 v[54:55], v[54:55], v[54:55] op_sel_hi:[0,1]
	v_pk_add_f32 v[46:47], v[46:47], v[46:47] op_sel_hi:[0,1]
	v_mul_f32_e32 v46, v134, v134
	v_pk_fma_f32 v[48:49], v[134:135], v[134:135], v[46:47] op_sel_hi:[1,1,0]
	v_mul_f32_e32 v46, v136, v136
	v_pk_fma_f32 v[56:57], v[136:137], v[136:137], v[46:47] op_sel_hi:[1,1,0]
	v_mul_f32_e32 v48, v138, v138
	v_mul_f32_e32 v56, v139, v139
	v_mul_f32_e32 v54, v140, v140
	v_mul_f32_e32 v46, v141, v141
	v_pk_add_f32 v[48:49], v[48:49], v[56:57]
	v_pk_add_f32 v[46:47], v[54:55], v[46:47]
	s_waitcnt vmcnt(10)
	v_pk_add_f32 v[54:55], v[66:67], 1.0 op_sel_hi:[1,0]
	v_pk_add_f32 v[46:47], v[48:49], v[46:47]
	v_pk_add_f32 v[48:49], v[68:69], 1.0 op_sel_hi:[1,0]
	v_add_f32_e32 v46, v46, v47
	s_nop 1
	v_add_f32_dpp v46, v46, v46 quad_perm:[1,0,3,2] row_mask:0xf bank_mask:0xf
	s_nop 1
	v_add_f32_dpp v46, v46, v46 quad_perm:[2,3,0,1] row_mask:0xf bank_mask:0xf
	s_nop 1
	v_add_f32_dpp v46, v46, v46 row_half_mirror row_mask:0xf bank_mask:0xf
	s_nop 1
	v_add_f32_dpp v46, v46, v46 row_mirror row_mask:0xf bank_mask:0xf
	s_nop 0
	v_readlane_b32 s64, v46, 0
	v_readlane_b32 s65, v46, 16
	v_readlane_b32 s66, v46, 32
	v_readlane_b32 s67, v46, 48
	v_mov_b32_e32 v47, s65
	v_add_f32_e32 v47, s64, v47
	v_mov_b32_e32 v46, s67
	v_add_f32_e32 v46, s66, v46
	v_add_f32_e32 v46, v47, v46
	s_waitcnt lgkmcnt(0)
	s_add_i32 s0, s23, 8
	s_add_i32 s1, s23, -8
	s_cmp_lt_i32 s1, s17
	s_mov_b32 s23, s0
	v_fmamk_f32 v46, v46, 0x3a800000, v192
	v_mul_f32_e32 v47, 0x4b800000, v46
	v_cmp_gt_f32_e32 vcc, s27, v46
	s_nop 1
	v_cndmask_b32_e32 v46, v46, v47, vcc
	v_rsq_f32_e32 v56, v46
	v_lshl_add_u64 v[46:47], v[158:159], 0, s[2:3]
	v_mul_f32_e32 v57, 0x45800000, v56
	v_cndmask_b32_e32 v56, v56, v57, vcc
	v_pk_mul_f32 v[58:59], v[80:81], v[56:57] op_sel_hi:[1,0]
	v_pk_mul_f32 v[60:61], v[78:79], v[56:57] op_sel_hi:[1,0]
	v_pk_mul_f32 v[58:59], v[12:13], v[58:59]
	v_pk_mul_f32 v[60:61], v[10:11], v[60:61]
	s_waitcnt vmcnt(9)
	v_pk_fma_f32 v[48:49], v[48:49], v[58:59], v[72:73]
	v_pk_fma_f32 v[54:55], v[54:55], v[60:61], v[70:71]
	v_pk_mul_f32 v[78:79], v[132:133], v[56:57] op_sel_hi:[1,0]
	v_pk_mul_f32 v[80:81], v[130:131], v[56:57] op_sel_hi:[1,0]
	v_cvt_pk_bf16_f32 v54, v54, v55
	v_cvt_pk_bf16_f32 v55, v48, v49
	v_pk_mul_f32 v[80:81], v[14:15], v[80:81]
	global_store_dwordx2 v[46:47], v[54:55], off
	v_pk_mul_f32 v[48:49], v[16:17], v[78:79]
	s_waitcnt vmcnt(6)
	v_pk_add_f32 v[54:55], v[76:77], 1.0 op_sel_hi:[1,0]
	v_pk_add_f32 v[58:59], v[74:75], 1.0 op_sel_hi:[1,0]
	v_pk_fma_f32 v[48:49], v[54:55], v[48:49], v[84:85]
	v_pk_fma_f32 v[54:55], v[58:59], v[80:81], v[82:83]
	s_waitcnt vmcnt(4)
	v_pk_add_f32 v[58:59], v[88:89], 1.0 op_sel_hi:[1,0]
	v_cvt_pk_bf16_f32 v54, v54, v55
	v_cvt_pk_bf16_f32 v55, v48, v49
	global_store_dwordx2 v[46:47], v[54:55], off offset:512
	v_pk_mul_f32 v[48:49], v[136:137], v[56:57] op_sel_hi:[1,0]
	v_pk_mul_f32 v[54:55], v[134:135], v[56:57] op_sel_hi:[1,0]
	v_pk_mul_f32 v[48:49], v[28:29], v[48:49]
	v_pk_mul_f32 v[54:55], v[26:27], v[54:55]
	v_pk_add_f32 v[60:61], v[86:87], 1.0 op_sel_hi:[1,0]
	s_waitcnt vmcnt(3)
	v_pk_fma_f32 v[48:49], v[58:59], v[48:49], v[96:97]
	v_pk_fma_f32 v[54:55], v[60:61], v[54:55], v[94:95]
	v_pk_add_f32 v[58:59], v[62:63], 1.0 op_sel_hi:[1,0]
	v_cvt_pk_bf16_f32 v54, v54, v55
	v_cvt_pk_bf16_f32 v55, v48, v49
	global_store_dwordx2 v[46:47], v[54:55], off offset:1024
	v_pk_mul_f32 v[48:49], v[140:141], v[56:57] op_sel_hi:[1,0]
	v_pk_mul_f32 v[54:55], v[138:139], v[56:57] op_sel_hi:[1,0]
	v_pk_mul_f32 v[48:49], v[32:33], v[48:49]
	v_pk_mul_f32 v[54:55], v[30:31], v[54:55]
	v_pk_add_f32 v[56:57], v[64:65], 1.0 op_sel_hi:[1,0]
	s_waitcnt vmcnt(3)
	v_pk_fma_f32 v[54:55], v[58:59], v[54:55], v[90:91]
	v_pk_fma_f32 v[48:49], v[56:57], v[48:49], v[92:93]
	v_cvt_pk_bf16_f32 v54, v54, v55
	v_cvt_pk_bf16_f32 v55, v48, v49
	global_store_dwordx2 v[46:47], v[54:55], off offset:1536
	s_mov_b64 vcc, s[98:99]
	s_cbranch_vccz .Leload_skip_0
	s_waitcnt vmcnt(8)
	v_lshlrev_b32_e32 v114, 16, v116
	v_and_b32_e32 v115, 0xffff0000, v116
	v_lshlrev_b32_e32 v116, 16, v117
	v_and_b32_e32 v117, 0xffff0000, v117
	v_lshlrev_b32_e32 v118, 16, v120
	v_and_b32_e32 v119, 0xffff0000, v120
	v_lshlrev_b32_e32 v120, 16, v121
	v_and_b32_e32 v121, 0xffff0000, v121
	v_lshlrev_b32_e32 v122, 16, v124
	v_and_b32_e32 v123, 0xffff0000, v124
	v_lshlrev_b32_e32 v124, 16, v125
	v_and_b32_e32 v125, 0xffff0000, v125
	v_lshlrev_b32_e32 v126, 16, v128
	v_and_b32_e32 v127, 0xffff0000, v128
	v_lshlrev_b32_e32 v128, 16, v129
	v_and_b32_e32 v129, 0xffff0000, v129

; #define GAS __attribute__((address_space(1)))
; DI unsigned pk2(float lo, float hi) { f32x2_t v = {lo, hi}; bf16x2_t b = __builtin_convertvector(v, bf16x2_t); return __builtin_bit_cast(unsigned, b); }
; DI float bflo(unsigned w) { return __uint_as_float(w << 16); }
; DI float bfhi(unsigned w) { return __uint_as_float(w & 0xffff0000u); }
; DI float wave_sum(float v) {
; #pragma unroll
;     for (int o = 1; o < 64; o <<= 1) v += __shfl_xor(v, o);
;     return v;
; }
; DI void phase_e(const Ctx& C, int nslab, int has_post, int pl, int ps, float pw, int has_pre, int ql, int qs, int nrows,
;                 const GAS float* xsrc, const GAS float* csrc, GAS float* xdst, GAS float* cdst, bool xs16, bool xd16) {
;     ...
;         if (has_post) {
;             f32x4 y[4]; float ss = 0.f;
; #pragma unroll
;             for (int j = 0; j < 4; ++j) {
;                 if (isx || nslab == 0) { y[j] = (f32x4){bflo(yw[j].x), bfhi(yw[j].x), bflo(yw[j].y), bfhi(yw[j].y)}; }
;                 else { y[j] = (f32x4){0.f, 0.f, 0.f, 0.f};
;                     for (int s = 0; s < nslab; ++s) { const u32x2 w = *(const GAS u32x2*)(YS + ((size_t)s * MC + (row - MX)) * 1024 + 256 * j + 4 * lane); y[j] += (f32x4){bflo(w.x), bfhi(w.x), bflo(w.y), bfhi(w.y)}; } }
;                 ss += (y[j][0] * y[j][0] + y[j][1] * y[j][1]) + (y[j][2] * y[j][2] + y[j][3] * y[j][3]); }
;             const float r = rsqrtf(wave_sum(ss) * (1.0f / 1024.0f) + EPS);
;             if (isx && xd16) { GAS bf16* d16 = (GAS bf16*)xdst + (size_t)row * 1024;
; #pragma unroll
;                 for (int j = 0; j < 4; ++j) { v[j] += pw * gt[j] * ((y[j] * r) * gpo[j]); u32x2 w; w.x = pk2(v[j][0], v[j][1]); w.y = pk2(v[j][2], v[j][3]); __builtin_nontemporal_store(w, (GAS u32x2*)(d16 + 256 * j + 4 * lane));
;                     v[j] = (f32x4){bflo(w.x), bfhi(w.x), bflo(w.y), bfhi(w.y)}; }
;             } else { GAS float* dst = isx ? xdst + (size_t)row * 1024 : cdst + (size_t)(row - MX) * 1024;
; #pragma unroll
;                 for (int j = 0; j < 4; ++j) { v[j] += pw * gt[j] * ((y[j] * r) * gpo[j]); __builtin_nontemporal_store(v[j], (GAS f32x4*)(dst + 256 * j + 4 * lane)); } }
.LBB0_971:
	v_mul_f32_e32 v130, v175, v175
	v_mul_f32_e32 v131, v139, v139
	v_fmac_f32_e32 v130, v174, v174
	v_fmac_f32_e32 v131, v138, v138
	v_add_f32_e32 v130, v130, v131
	v_mul_f32_e32 v131, v171, v171
	v_mul_f32_e32 v132, v173, v173
	v_fmac_f32_e32 v131, v170, v170
	v_fmac_f32_e32 v132, v172, v172
	v_add_f32_e32 v131, v131, v132
	v_add_f32_e32 v130, v130, v131
	v_mul_f32_e32 v131, v177, v177
	v_mul_f32_e32 v132, v179, v179
	v_fmac_f32_e32 v131, v176, v176
	v_fmac_f32_e32 v132, v178, v178
	v_add_f32_e32 v131, v131, v132
	v_add_f32_e32 v136, v130, v131
	v_pk_mul_f32 v[130:131], v[182:183], v[182:183]
	v_pk_mul_f32 v[132:133], v[180:181], v[180:181]
	s_and_b64 s[0:1], exec, s[0:1]
	v_pk_mov_b32 v[134:135], v[132:133], v[130:131] op_sel:[1,0]
	v_mov_b32_e32 v133, v131
	v_pk_add_f32 v[130:131], v[134:135], v[132:133]
	s_ashr_i32 s11, s10, 31
	v_add_f32_e32 v130, v130, v131
	v_add_f32_e32 v130, v136, v130
	s_nop 1
	v_add_f32_dpp v130, v130, v130 quad_perm:[1,0,3,2] row_mask:0xf bank_mask:0xf
	s_nop 1
	v_add_f32_dpp v130, v130, v130 quad_perm:[2,3,0,1] row_mask:0xf bank_mask:0xf
	s_nop 1
	v_add_f32_dpp v130, v130, v130 row_half_mirror row_mask:0xf bank_mask:0xf
	s_nop 1
	v_add_f32_dpp v130, v130, v130 row_mirror row_mask:0xf bank_mask:0xf
	s_nop 0
	v_readlane_b32 s64, v130, 0
	v_readlane_b32 s65, v130, 16
	v_readlane_b32 s66, v130, 32
	v_readlane_b32 s67, v130, 48
	v_mov_b32_e32 v131, s65
	v_add_f32_e32 v131, s64, v131
	v_mov_b32_e32 v130, s67
	v_add_f32_e32 v130, s66, v130
	v_add_f32_e32 v130, v131, v130
	s_waitcnt lgkmcnt(0)
	s_mov_b64 s[12:13], -1
	v_fmamk_f32 v130, v130, 0x3a800000, v192
	v_mul_f32_e32 v131, 0x4b800000, v130
	v_cmp_gt_f32_e32 vcc, s27, v130
	s_nop 1
	v_cndmask_b32_e32 v130, v130, v131, vcc
	v_rsq_f32_e32 v130, v130
	s_nop 0
	v_mul_f32_e32 v131, 0x45800000, v130
	v_cndmask_b32_e32 v184, v130, v131, vcc
	v_mov_b32_e32 v185, v184
	v_pk_mul_f32 v[130:131], v[138:139], v[184:185] op_sel_hi:[1,0]
	v_pk_mul_f32 v[134:135], v[174:175], v[184:185] op_sel_hi:[1,0]
	v_pk_mul_f32 v[130:131], v[4:5], v[130:131]
	v_pk_mul_f32 v[134:135], v[2:3], v[134:135]
	s_waitcnt vmcnt(11)
	v_pk_fma_f32 v[80:81], v[100:101], v[130:131], v[80:81]
	v_pk_fma_f32 v[78:79], v[98:99], v[134:135], v[78:79]
	s_mov_b64 vcc, s[0:1]
	s_cbranch_vccz .LBB0_973
	v_mov_b32_e32 v138, v184
	v_mov_b32_e32 v139, v184
	v_pk_mul_f32 v[130:131], v[172:173], v[138:139]
	v_pk_mul_f32 v[132:133], v[170:171], v[184:185]
	v_pk_mul_f32 v[130:131], v[8:9], v[130:131]
	v_pk_mul_f32 v[134:135], v[6:7], v[132:133]
	s_waitcnt vmcnt(7)
	v_pk_fma_f32 v[132:133], v[104:105], v[130:131], v[60:61]
	v_pk_fma_f32 v[130:131], v[102:103], v[134:135], v[58:59]
	v_pk_mul_f32 v[134:135], v[178:179], v[138:139]
	v_pk_mul_f32 v[136:137], v[176:177], v[184:185]
	v_pk_mul_f32 v[134:135], v[20:21], v[134:135]
	v_pk_mul_f32 v[140:141], v[18:19], v[136:137]
	s_waitcnt vmcnt(6)
	v_pk_fma_f32 v[136:137], v[108:109], v[134:135], v[56:57]
	v_pk_fma_f32 v[134:135], v[106:107], v[140:141], v[54:55]
	v_pk_mul_f32 v[138:139], v[182:183], v[138:139]
	v_pk_mul_f32 v[140:141], v[180:181], v[184:185]
	s_lshl_b64 s[0:1], s[4:5], 12
	v_pk_mul_f32 v[138:139], v[24:25], v[138:139]
	v_pk_mul_f32 v[194:195], v[22:23], v[140:141]
	v_lshl_add_u64 v[174:175], v[160:161], 0, s[0:1]
	s_waitcnt vmcnt(4)
	v_pk_fma_f32 v[140:141], v[112:113], v[138:139], v[48:49]
	v_pk_fma_f32 v[138:139], v[110:111], v[194:195], v[46:47]
	global_store_dwordx4 v[174:175], v[78:81], off nt
	global_store_dwordx4 v[174:175], v[130:133], off offset:1024 nt
	global_store_dwordx4 v[174:175], v[134:137], off offset:2048 nt
	global_store_dwordx4 v[174:175], v[138:141], off offset:3072 nt
	s_lshl_b64 s[2:3], s[10:11], 11
	s_mov_b64 s[12:13], 0

; #define GAS __attribute__((address_space(1)))
; DI unsigned pk2(float lo, float hi) { f32x2_t v = {lo, hi}; bf16x2_t b = __builtin_convertvector(v, bf16x2_t); return __builtin_bit_cast(unsigned, b); }
; DI float wave_sum(float v) {
; #pragma unroll
;     for (int o = 1; o < 64; o <<= 1) v += __shfl_xor(v, o);
;     return v;
; }
; DI void phase_e(const Ctx& C, int nslab, int has_post, int pl, int ps, float pw, int has_pre, int ql, int qs, int nrows,
;                 const GAS float* xsrc, const GAS float* csrc, GAS float* xdst, GAS float* cdst, bool xs16, bool xd16) {
;     ...
;         if (has_pre) {
;             float ss = 0.f;
; #pragma unroll
;             for (int j = 0; j < 4; ++j) ss += (v[j][0] * v[j][0] + v[j][1] * v[j][1]) + (v[j][2] * v[j][2] + v[j][3] * v[j][3]);
;             const float r = rsqrtf(wave_sum(ss) * (1.0f / 1024.0f) + EPS);
; #pragma unroll
;             for (int j = 0; j < 4; ++j) { const f32x4 h = ((v[j] * r) * gpr[j]) * (1.0f + sc[j]) + sh[j];
;                 u32x2 w; w.x = pk2(h[0], h[1]); w.y = pk2(h[2], h[3]); *(GAS u32x2*)(H + (size_t)row * 1024 + 256 * j + 4 * lane) = w; }
;         }
.LBB0_1212:
	v_pk_mul_f32 v[54:55], v[100:101], v[100:101]
	v_pk_mul_f32 v[56:57], v[98:99], v[98:99]
	v_pk_mul_f32 v[46:47], v[132:133], v[132:133]
	v_pk_mul_f32 v[48:49], v[130:131], v[130:131]
	v_pk_mov_b32 v[58:59], v[56:57], v[54:55] op_sel:[1,0]
	v_mov_b32_e32 v57, v55
	v_pk_add_f32 v[54:55], v[58:59], v[56:57]
	v_pk_mov_b32 v[56:57], v[48:49], v[46:47] op_sel:[1,0]
	v_mov_b32_e32 v49, v47
	v_pk_add_f32 v[46:47], v[56:57], v[48:49]
	v_pk_add_f32 v[54:55], v[54:55], v[54:55] op_sel_hi:[0,1]
	v_pk_add_f32 v[46:47], v[46:47], v[46:47] op_sel_hi:[0,1]
	v_mul_f32_e32 v46, v134, v134
	v_pk_fma_f32 v[48:49], v[134:135], v[134:135], v[46:47] op_sel_hi:[1,1,0]
	v_mul_f32_e32 v46, v136, v136
	v_pk_fma_f32 v[56:57], v[136:137], v[136:137], v[46:47] op_sel_hi:[1,1,0]
	v_mul_f32_e32 v48, v138, v138
	v_mul_f32_e32 v56, v139, v139
	v_mul_f32_e32 v54, v140, v140
	v_mul_f32_e32 v46, v141, v141
	v_pk_add_f32 v[48:49], v[48:49], v[56:57]
	v_pk_add_f32 v[46:47], v[54:55], v[46:47]
	v_pk_add_f32 v[54:55], v[66:67], 1.0 op_sel_hi:[1,0]
	v_pk_add_f32 v[46:47], v[48:49], v[46:47]
	v_pk_add_f32 v[48:49], v[68:69], 1.0 op_sel_hi:[1,0]
	v_add_f32_e32 v46, v46, v47
	s_nop 1
	v_add_f32_dpp v46, v46, v46 quad_perm:[1,0,3,2] row_mask:0xf bank_mask:0xf
	s_nop 1
	v_add_f32_dpp v46, v46, v46 quad_perm:[2,3,0,1] row_mask:0xf bank_mask:0xf
	s_nop 1
	v_add_f32_dpp v46, v46, v46 row_half_mirror row_mask:0xf bank_mask:0xf
	s_nop 1
	v_add_f32_dpp v46, v46, v46 row_mirror row_mask:0xf bank_mask:0xf
	s_nop 0
	v_readlane_b32 s64, v46, 0
	v_readlane_b32 s65, v46, 16
	v_readlane_b32 s66, v46, 32
	v_readlane_b32 s67, v46, 48
	v_mov_b32_e32 v47, s65
	v_add_f32_e32 v47, s64, v47
	v_mov_b32_e32 v46, s67
	v_add_f32_e32 v46, s66, v46
	v_add_f32_e32 v46, v47, v46
	s_waitcnt lgkmcnt(0)
	s_add_i32 s0, s22, 8
	s_add_i32 s1, s22, -8
	s_cmp_lt_i32 s1, s17
	s_mov_b32 s22, s0
	v_mov_b64_e32 v[170:171], v[144:145]
	s_waitcnt vmcnt(3)
	v_mov_b64_e32 v[144:145], v[162:163]
	v_fmamk_f32 v46, v46, 0x3a800000, v196
	v_mul_f32_e32 v47, 0x4b800000, v46
	v_cmp_gt_f32_e32 vcc, s25, v46
	s_nop 1
	v_cndmask_b32_e32 v46, v46, v47, vcc
	v_rsq_f32_e32 v56, v46
	v_lshl_add_u64 v[46:47], v[158:159], 0, s[2:3]
	v_mul_f32_e32 v57, 0x45800000, v56
	v_cndmask_b32_e32 v56, v56, v57, vcc
	v_pk_mul_f32 v[58:59], v[100:101], v[56:57] op_sel_hi:[1,0]
	v_pk_mul_f32 v[60:61], v[98:99], v[56:57] op_sel_hi:[1,0]
	v_pk_mul_f32 v[58:59], v[12:13], v[58:59]
	v_pk_mul_f32 v[60:61], v[10:11], v[60:61]
	v_pk_fma_f32 v[48:49], v[48:49], v[58:59], v[72:73]
	v_pk_fma_f32 v[54:55], v[54:55], v[60:61], v[70:71]
	v_pk_mul_f32 v[98:99], v[132:133], v[56:57] op_sel_hi:[1,0]
	v_pk_mul_f32 v[100:101], v[130:131], v[56:57] op_sel_hi:[1,0]
	v_cvt_pk_bf16_f32 v54, v54, v55
	v_cvt_pk_bf16_f32 v55, v48, v49
	v_pk_mul_f32 v[100:101], v[14:15], v[100:101]
	global_store_dwordx2 v[46:47], v[54:55], off
	v_pk_mul_f32 v[48:49], v[16:17], v[98:99]
	v_pk_add_f32 v[54:55], v[76:77], 1.0 op_sel_hi:[1,0]
	v_pk_add_f32 v[58:59], v[74:75], 1.0 op_sel_hi:[1,0]
	v_pk_fma_f32 v[48:49], v[54:55], v[48:49], v[80:81]
	v_pk_fma_f32 v[54:55], v[58:59], v[100:101], v[78:79]
	v_pk_add_f32 v[58:59], v[84:85], 1.0 op_sel_hi:[1,0]
	v_cvt_pk_bf16_f32 v54, v54, v55
	v_cvt_pk_bf16_f32 v55, v48, v49
	global_store_dwordx2 v[46:47], v[54:55], off offset:512
	v_pk_mul_f32 v[48:49], v[136:137], v[56:57] op_sel_hi:[1,0]
	v_pk_mul_f32 v[54:55], v[134:135], v[56:57] op_sel_hi:[1,0]
	v_pk_mul_f32 v[48:49], v[28:29], v[48:49]
	v_pk_mul_f32 v[54:55], v[26:27], v[54:55]
	v_pk_add_f32 v[60:61], v[82:83], 1.0 op_sel_hi:[1,0]
	s_waitcnt vmcnt(3)
	v_pk_fma_f32 v[48:49], v[58:59], v[48:49], v[92:93]
	v_pk_fma_f32 v[54:55], v[60:61], v[54:55], v[90:91]
	v_pk_add_f32 v[58:59], v[62:63], 1.0 op_sel_hi:[1,0]
	v_cvt_pk_bf16_f32 v54, v54, v55
	v_cvt_pk_bf16_f32 v55, v48, v49
	global_store_dwordx2 v[46:47], v[54:55], off offset:1024
	v_pk_mul_f32 v[48:49], v[140:141], v[56:57] op_sel_hi:[1,0]
	v_pk_mul_f32 v[54:55], v[138:139], v[56:57] op_sel_hi:[1,0]
	v_pk_mul_f32 v[48:49], v[32:33], v[48:49]
	v_pk_mul_f32 v[54:55], v[30:31], v[54:55]
	v_pk_add_f32 v[56:57], v[64:65], 1.0 op_sel_hi:[1,0]
	s_waitcnt vmcnt(3)
	v_pk_fma_f32 v[54:55], v[58:59], v[54:55], v[86:87]
	v_pk_fma_f32 v[48:49], v[56:57], v[48:49], v[88:89]
	v_cvt_pk_bf16_f32 v54, v54, v55
	v_cvt_pk_bf16_f32 v55, v48, v49
	global_store_dwordx2 v[46:47], v[54:55], off offset:1536
	s_mov_b64 vcc, s[98:99]
	s_cbranch_vccz .Leload_skip_1
	s_waitcnt vmcnt(8)
	v_lshlrev_b32_e32 v114, 16, v116
	v_and_b32_e32 v115, 0xffff0000, v116
	v_lshlrev_b32_e32 v116, 16, v117
	v_and_b32_e32 v117, 0xffff0000, v117
	v_lshlrev_b32_e32 v118, 16, v120
	v_and_b32_e32 v119, 0xffff0000, v120
	v_lshlrev_b32_e32 v120, 16, v121
	v_and_b32_e32 v121, 0xffff0000, v121
	v_lshlrev_b32_e32 v122, 16, v124
	v_and_b32_e32 v123, 0xffff0000, v124
	v_lshlrev_b32_e32 v124, 16, v125
	v_and_b32_e32 v125, 0xffff0000, v125
	v_lshlrev_b32_e32 v126, 16, v128
	v_and_b32_e32 v127, 0xffff0000, v128
	v_lshlrev_b32_e32 v128, 16, v129
	v_and_b32_e32 v129, 0xffff0000, v129

; #define GAS __attribute__((address_space(1)))
; DI unsigned pk2(float lo, float hi) { f32x2_t v = {lo, hi}; bf16x2_t b = __builtin_convertvector(v, bf16x2_t); return __builtin_bit_cast(unsigned, b); }
; DI float bflo(unsigned w) { return __uint_as_float(w << 16); }
; DI float bfhi(unsigned w) { return __uint_as_float(w & 0xffff0000u); }
; DI float wave_sum(float v) {
; #pragma unroll
;     for (int o = 1; o < 64; o <<= 1) v += __shfl_xor(v, o);
;     return v;
; }
; DI void phase_e(const Ctx& C, int nslab, int has_post, int pl, int ps, float pw, int has_pre, int ql, int qs, int nrows,
;                 const GAS float* xsrc, const GAS float* csrc, GAS float* xdst, GAS float* cdst, bool xs16, bool xd16) {
;     ...
;         if (has_post) {
;             f32x4 y[4]; float ss = 0.f;
; #pragma unroll
;             for (int j = 0; j < 4; ++j) {
;                 if (isx || nslab == 0) { y[j] = (f32x4){bflo(yw[j].x), bfhi(yw[j].x), bflo(yw[j].y), bfhi(yw[j].y)}; }
;                 else { y[j] = (f32x4){0.f, 0.f, 0.f, 0.f};
;                     for (int s = 0; s < nslab; ++s) { const u32x2 w = *(const GAS u32x2*)(YS + ((size_t)s * MC + (row - MX)) * 1024 + 256 * j + 4 * lane); y[j] += (f32x4){bflo(w.x), bfhi(w.x), bflo(w.y), bfhi(w.y)}; } }
;                 ss += (y[j][0] * y[j][0] + y[j][1] * y[j][1]) + (y[j][2] * y[j][2] + y[j][3] * y[j][3]); }
;             const float r = rsqrtf(wave_sum(ss) * (1.0f / 1024.0f) + EPS);
;             if (isx && xd16) { GAS bf16* d16 = (GAS bf16*)xdst + (size_t)row * 1024;
; #pragma unroll
;                 for (int j = 0; j < 4; ++j) { v[j] += pw * gt[j] * ((y[j] * r) * gpo[j]); u32x2 w; w.x = pk2(v[j][0], v[j][1]); w.y = pk2(v[j][2], v[j][3]); __builtin_nontemporal_store(w, (GAS u32x2*)(d16 + 256 * j + 4 * lane));
;                     v[j] = (f32x4){bflo(w.x), bfhi(w.x), bflo(w.y), bfhi(w.y)}; }
;             } else { GAS float* dst = isx ? xdst + (size_t)row * 1024 : cdst + (size_t)(row - MX) * 1024;
; #pragma unroll
;                 for (int j = 0; j < 4; ++j) { v[j] += pw * gt[j] * ((y[j] * r) * gpo[j]); __builtin_nontemporal_store(v[j], (GAS f32x4*)(dst + 256 * j + 4 * lane)); } }
.LBB0_1238:
	v_mul_f32_e32 v130, v141, v141
	v_mul_f32_e32 v131, v139, v139
	v_fmac_f32_e32 v130, v140, v140
	v_fmac_f32_e32 v131, v138, v138
	v_add_f32_e32 v130, v130, v131
	v_mul_f32_e32 v131, v171, v171
	v_mul_f32_e32 v132, v173, v173
	v_fmac_f32_e32 v131, v170, v170
	v_fmac_f32_e32 v132, v172, v172
	v_add_f32_e32 v131, v131, v132
	v_add_f32_e32 v130, v130, v131
	v_mul_f32_e32 v131, v175, v175
	v_mul_f32_e32 v132, v177, v177
	v_fmac_f32_e32 v131, v174, v174
	v_fmac_f32_e32 v132, v176, v176
	v_add_f32_e32 v131, v131, v132
	v_add_f32_e32 v136, v130, v131
	v_pk_mul_f32 v[130:131], v[180:181], v[180:181]
	v_pk_mul_f32 v[132:133], v[178:179], v[178:179]
	s_and_b64 s[0:1], exec, s[0:1]
	v_pk_mov_b32 v[134:135], v[132:133], v[130:131] op_sel:[1,0]
	v_mov_b32_e32 v133, v131
	v_pk_add_f32 v[130:131], v[134:135], v[132:133]
	s_ashr_i32 s11, s10, 31
	v_add_f32_e32 v130, v130, v131
	v_add_f32_e32 v130, v136, v130
	s_nop 1
	v_add_f32_dpp v130, v130, v130 quad_perm:[1,0,3,2] row_mask:0xf bank_mask:0xf
	s_nop 1
	v_add_f32_dpp v130, v130, v130 quad_perm:[2,3,0,1] row_mask:0xf bank_mask:0xf
	s_nop 1
	v_add_f32_dpp v130, v130, v130 row_half_mirror row_mask:0xf bank_mask:0xf
	s_nop 1
	v_add_f32_dpp v130, v130, v130 row_mirror row_mask:0xf bank_mask:0xf
	s_nop 0
	v_readlane_b32 s64, v130, 0
	v_readlane_b32 s65, v130, 16
	v_readlane_b32 s66, v130, 32
	v_readlane_b32 s67, v130, 48
	v_mov_b32_e32 v131, s65
	v_add_f32_e32 v131, s64, v131
	v_mov_b32_e32 v130, s67
	v_add_f32_e32 v130, s66, v130
	v_add_f32_e32 v132, v131, v130
	s_waitcnt lgkmcnt(0)
	s_mov_b64 s[12:13], -1
	s_waitcnt vmcnt(7)
	v_pk_mul_f32 v[188:189], v[102:103], 0.5 op_sel_hi:[1,0]
	s_waitcnt vmcnt(6)
	v_pk_mul_f32 v[186:187], v[106:107], 0.5 op_sel_hi:[1,0]
	s_waitcnt vmcnt(4)
	v_pk_mul_f32 v[184:185], v[110:111], 0.5 op_sel_hi:[1,0]
	v_pk_mul_f32 v[130:131], v[96:97], 0.5 op_sel_hi:[1,0]
	v_fmamk_f32 v132, v132, 0x3a800000, v196
	v_mul_f32_e32 v133, 0x4b800000, v132
	v_cmp_gt_f32_e32 vcc, s25, v132
	s_nop 1
	v_cndmask_b32_e32 v132, v132, v133, vcc
	v_rsq_f32_e32 v134, v132
	v_pk_mul_f32 v[132:133], v[94:95], 0.5 op_sel_hi:[1,0]
	v_mul_f32_e32 v135, 0x45800000, v134
	v_cndmask_b32_e32 v182, v134, v135, vcc
	v_mov_b32_e32 v183, v182
	v_pk_mul_f32 v[134:135], v[138:139], v[182:183] op_sel_hi:[1,0]
	v_pk_mul_f32 v[136:137], v[140:141], v[182:183] op_sel_hi:[1,0]
	v_pk_mul_f32 v[134:135], v[4:5], v[134:135]
	v_pk_mul_f32 v[136:137], v[2:3], v[136:137]
	v_pk_fma_f32 v[100:101], v[130:131], v[134:135], v[100:101]
	v_pk_fma_f32 v[98:99], v[132:133], v[136:137], v[98:99]
	s_mov_b64 vcc, s[0:1]
	s_cbranch_vccz .LBB0_1240
	v_mov_b32_e32 v138, v182
	v_mov_b32_e32 v139, v182
	v_pk_mul_f32 v[132:133], v[172:173], v[138:139]
	v_pk_mul_f32 v[134:135], v[170:171], v[182:183]
	v_pk_mul_f32 v[130:131], v[104:105], 0.5 op_sel_hi:[1,0]
	v_pk_mul_f32 v[132:133], v[8:9], v[132:133]
	v_pk_mul_f32 v[134:135], v[6:7], v[134:135]
	v_pk_mul_f32 v[136:137], v[176:177], v[138:139]
	v_pk_mul_f32 v[140:141], v[174:175], v[182:183]
	v_pk_fma_f32 v[132:133], v[130:131], v[132:133], v[60:61]
	v_pk_fma_f32 v[130:131], v[188:189], v[134:135], v[58:59]
	v_pk_mul_f32 v[134:135], v[108:109], 0.5 op_sel_hi:[1,0]
	v_pk_mul_f32 v[136:137], v[20:21], v[136:137]
	v_pk_mul_f32 v[140:141], v[18:19], v[140:141]
	v_pk_mul_f32 v[138:139], v[180:181], v[138:139]
	v_pk_mul_f32 v[200:201], v[178:179], v[182:183]
	s_lshl_b64 s[0:1], s[4:5], 12
	v_pk_fma_f32 v[136:137], v[134:135], v[136:137], v[56:57]
	v_pk_fma_f32 v[134:135], v[186:187], v[140:141], v[54:55]
	v_pk_mul_f32 v[140:141], v[112:113], 0.5 op_sel_hi:[1,0]
	v_pk_mul_f32 v[138:139], v[24:25], v[138:139]
	v_pk_mul_f32 v[200:201], v[22:23], v[200:201]
	v_lshl_add_u64 v[198:199], v[160:161], 0, s[0:1]
	v_pk_fma_f32 v[140:141], v[140:141], v[138:139], v[48:49]
	v_pk_fma_f32 v[138:139], v[184:185], v[200:201], v[46:47]
	global_store_dwordx4 v[198:199], v[98:101], off nt
	global_store_dwordx4 v[198:199], v[130:133], off offset:1024 nt
	global_store_dwordx4 v[198:199], v[134:137], off offset:2048 nt
	global_store_dwordx4 v[198:199], v[138:141], off offset:3072 nt
	s_lshl_b64 s[2:3], s[10:11], 11
	s_mov_b64 s[12:13], 0

; #define GAS __attribute__((address_space(1)))
; DI unsigned pk2(float lo, float hi) { f32x2_t v = {lo, hi}; bf16x2_t b = __builtin_convertvector(v, bf16x2_t); return __builtin_bit_cast(unsigned, b); }
; DI float wave_sum(float v) {
; #pragma unroll
;     for (int o = 1; o < 64; o <<= 1) v += __shfl_xor(v, o);
;     return v;
; }
; DI void phase_e(const Ctx& C, int nslab, int has_post, int pl, int ps, float pw, int has_pre, int ql, int qs, int nrows,
;                 const GAS float* xsrc, const GAS float* csrc, GAS float* xdst, GAS float* cdst, bool xs16, bool xd16) {
;     ...
;         if (has_pre) {
;             float ss = 0.f;
; #pragma unroll
;             for (int j = 0; j < 4; ++j) ss += (v[j][0] * v[j][0] + v[j][1] * v[j][1]) + (v[j][2] * v[j][2] + v[j][3] * v[j][3]);
;             const float r = rsqrtf(wave_sum(ss) * (1.0f / 1024.0f) + EPS);
; #pragma unroll
;             for (int j = 0; j < 4; ++j) { const f32x4 h = ((v[j] * r) * gpr[j]) * (1.0f + sc[j]) + sh[j];
;                 u32x2 w; w.x = pk2(h[0], h[1]); w.y = pk2(h[2], h[3]); *(GAS u32x2*)(H + (size_t)row * 1024 + 256 * j + 4 * lane) = w; }
;         }
.LBB0_1480:
	v_pk_mul_f32 v[54:55], v[100:101], v[100:101]
	v_pk_mul_f32 v[56:57], v[98:99], v[98:99]
	v_pk_mul_f32 v[46:47], v[132:133], v[132:133]
	v_pk_mul_f32 v[48:49], v[130:131], v[130:131]
	v_pk_mov_b32 v[58:59], v[56:57], v[54:55] op_sel:[1,0]
	v_mov_b32_e32 v57, v55
	v_pk_add_f32 v[54:55], v[58:59], v[56:57]
	v_pk_mov_b32 v[56:57], v[48:49], v[46:47] op_sel:[1,0]
	v_mov_b32_e32 v49, v47
	v_pk_add_f32 v[46:47], v[56:57], v[48:49]
	v_pk_add_f32 v[54:55], v[54:55], v[54:55] op_sel_hi:[0,1]
	v_pk_add_f32 v[46:47], v[46:47], v[46:47] op_sel_hi:[0,1]
	v_mul_f32_e32 v46, v134, v134
	v_pk_fma_f32 v[48:49], v[134:135], v[134:135], v[46:47] op_sel_hi:[1,1,0]
	v_mul_f32_e32 v46, v136, v136
	v_pk_fma_f32 v[56:57], v[136:137], v[136:137], v[46:47] op_sel_hi:[1,1,0]
	v_mul_f32_e32 v48, v138, v138
	v_mul_f32_e32 v56, v139, v139
	v_mul_f32_e32 v54, v140, v140
	v_mul_f32_e32 v46, v141, v141
	v_pk_add_f32 v[48:49], v[48:49], v[56:57]
	v_pk_add_f32 v[46:47], v[54:55], v[46:47]
	v_pk_add_f32 v[54:55], v[66:67], 1.0 op_sel_hi:[1,0]
	v_pk_add_f32 v[46:47], v[48:49], v[46:47]
	v_pk_add_f32 v[48:49], v[68:69], 1.0 op_sel_hi:[1,0]
	v_add_f32_e32 v46, v46, v47
	s_nop 1
	v_add_f32_dpp v46, v46, v46 quad_perm:[1,0,3,2] row_mask:0xf bank_mask:0xf
	s_nop 1
	v_add_f32_dpp v46, v46, v46 quad_perm:[2,3,0,1] row_mask:0xf bank_mask:0xf
	s_nop 1
	v_add_f32_dpp v46, v46, v46 row_half_mirror row_mask:0xf bank_mask:0xf
	s_nop 1
	v_add_f32_dpp v46, v46, v46 row_mirror row_mask:0xf bank_mask:0xf
	s_nop 0
	v_readlane_b32 s64, v46, 0
	v_readlane_b32 s65, v46, 16
	v_readlane_b32 s66, v46, 32
	v_readlane_b32 s67, v46, 48
	v_mov_b32_e32 v47, s65
	v_add_f32_e32 v47, s64, v47
	v_mov_b32_e32 v46, s67
	v_add_f32_e32 v46, s66, v46
	v_add_f32_e32 v46, v47, v46
	s_waitcnt lgkmcnt(0)
	s_add_i32 s0, s23, 8
	s_add_i32 s1, s23, -8
	s_cmp_lt_i32 s1, s17
	s_mov_b32 s23, s0
	v_mov_b64_e32 v[170:171], v[144:145]
	s_waitcnt vmcnt(3)
	v_mov_b64_e32 v[144:145], v[162:163]
	v_fmamk_f32 v46, v46, 0x3a800000, v196
	v_mul_f32_e32 v47, 0x4b800000, v46
	v_cmp_gt_f32_e32 vcc, s27, v46
	s_nop 1
	v_cndmask_b32_e32 v46, v46, v47, vcc
	v_rsq_f32_e32 v56, v46
	v_lshl_add_u64 v[46:47], v[158:159], 0, s[2:3]
	v_mul_f32_e32 v57, 0x45800000, v56
	v_cndmask_b32_e32 v56, v56, v57, vcc
	v_pk_mul_f32 v[58:59], v[100:101], v[56:57] op_sel_hi:[1,0]
	v_pk_mul_f32 v[60:61], v[98:99], v[56:57] op_sel_hi:[1,0]
	v_pk_mul_f32 v[58:59], v[12:13], v[58:59]
	v_pk_mul_f32 v[60:61], v[10:11], v[60:61]
	v_pk_fma_f32 v[48:49], v[48:49], v[58:59], v[72:73]
	v_pk_fma_f32 v[54:55], v[54:55], v[60:61], v[70:71]
	v_pk_mul_f32 v[98:99], v[132:133], v[56:57] op_sel_hi:[1,0]
	v_pk_mul_f32 v[100:101], v[130:131], v[56:57] op_sel_hi:[1,0]
	v_cvt_pk_bf16_f32 v54, v54, v55
	v_cvt_pk_bf16_f32 v55, v48, v49
	v_pk_mul_f32 v[100:101], v[14:15], v[100:101]
	global_store_dwordx2 v[46:47], v[54:55], off
	v_pk_mul_f32 v[48:49], v[16:17], v[98:99]
	v_pk_add_f32 v[54:55], v[76:77], 1.0 op_sel_hi:[1,0]
	v_pk_add_f32 v[58:59], v[74:75], 1.0 op_sel_hi:[1,0]
	v_pk_fma_f32 v[48:49], v[54:55], v[48:49], v[80:81]
	v_pk_fma_f32 v[54:55], v[58:59], v[100:101], v[78:79]
	v_pk_add_f32 v[58:59], v[84:85], 1.0 op_sel_hi:[1,0]
	v_cvt_pk_bf16_f32 v54, v54, v55
	v_cvt_pk_bf16_f32 v55, v48, v49
	global_store_dwordx2 v[46:47], v[54:55], off offset:512
	v_pk_mul_f32 v[48:49], v[136:137], v[56:57] op_sel_hi:[1,0]
	v_pk_mul_f32 v[54:55], v[134:135], v[56:57] op_sel_hi:[1,0]
	v_pk_mul_f32 v[48:49], v[28:29], v[48:49]
	v_pk_mul_f32 v[54:55], v[26:27], v[54:55]
	v_pk_add_f32 v[60:61], v[82:83], 1.0 op_sel_hi:[1,0]
	s_waitcnt vmcnt(3)
	v_pk_fma_f32 v[48:49], v[58:59], v[48:49], v[92:93]
	v_pk_fma_f32 v[54:55], v[60:61], v[54:55], v[90:91]
	v_pk_add_f32 v[58:59], v[62:63], 1.0 op_sel_hi:[1,0]
	v_cvt_pk_bf16_f32 v54, v54, v55
	v_cvt_pk_bf16_f32 v55, v48, v49
	global_store_dwordx2 v[46:47], v[54:55], off offset:1024
	v_pk_mul_f32 v[48:49], v[140:141], v[56:57] op_sel_hi:[1,0]
	v_pk_mul_f32 v[54:55], v[138:139], v[56:57] op_sel_hi:[1,0]
	v_pk_mul_f32 v[48:49], v[32:33], v[48:49]
	v_pk_mul_f32 v[54:55], v[30:31], v[54:55]
	v_pk_add_f32 v[56:57], v[64:65], 1.0 op_sel_hi:[1,0]
	s_waitcnt vmcnt(3)
	v_pk_fma_f32 v[54:55], v[58:59], v[54:55], v[86:87]
	v_pk_fma_f32 v[48:49], v[56:57], v[48:49], v[88:89]
	v_cvt_pk_bf16_f32 v54, v54, v55
	v_cvt_pk_bf16_f32 v55, v48, v49
	global_store_dwordx2 v[46:47], v[54:55], off offset:1536
	s_mov_b64 vcc, s[98:99]
	s_cbranch_vccz .Leload_skip_2
	s_waitcnt vmcnt(8)
	v_lshlrev_b32_e32 v114, 16, v116
	v_and_b32_e32 v115, 0xffff0000, v116
	v_lshlrev_b32_e32 v116, 16, v117
	v_and_b32_e32 v117, 0xffff0000, v117
	v_lshlrev_b32_e32 v118, 16, v120
	v_and_b32_e32 v119, 0xffff0000, v120
	v_lshlrev_b32_e32 v120, 16, v121
	v_and_b32_e32 v121, 0xffff0000, v121
	v_lshlrev_b32_e32 v122, 16, v124
	v_and_b32_e32 v123, 0xffff0000, v124
	v_lshlrev_b32_e32 v124, 16, v125
	v_and_b32_e32 v125, 0xffff0000, v125
	v_lshlrev_b32_e32 v126, 16, v128
	v_and_b32_e32 v127, 0xffff0000, v128
	v_lshlrev_b32_e32 v128, 16, v129
	v_and_b32_e32 v129, 0xffff0000, v129

; #define GAS __attribute__((address_space(1)))
; DI unsigned pk2(float lo, float hi) { f32x2_t v = {lo, hi}; bf16x2_t b = __builtin_convertvector(v, bf16x2_t); return __builtin_bit_cast(unsigned, b); }
; DI float bflo(unsigned w) { return __uint_as_float(w << 16); }
; DI float bfhi(unsigned w) { return __uint_as_float(w & 0xffff0000u); }
; DI float wave_sum(float v) {
; #pragma unroll
;     for (int o = 1; o < 64; o <<= 1) v += __shfl_xor(v, o);
;     return v;
; }
; DI void phase_e(const Ctx& C, int nslab, int has_post, int pl, int ps, float pw, int has_pre, int ql, int qs, int nrows,
;                 const GAS float* xsrc, const GAS float* csrc, GAS float* xdst, GAS float* cdst, bool xs16, bool xd16) {
;     ...
;         if (has_post) {
;             f32x4 y[4]; float ss = 0.f;
; #pragma unroll
;             for (int j = 0; j < 4; ++j) {
;                 if (isx || nslab == 0) { y[j] = (f32x4){bflo(yw[j].x), bfhi(yw[j].x), bflo(yw[j].y), bfhi(yw[j].y)}; }
;                 else { y[j] = (f32x4){0.f, 0.f, 0.f, 0.f};
;                     for (int s = 0; s < nslab; ++s) { const u32x2 w = *(const GAS u32x2*)(YS + ((size_t)s * MC + (row - MX)) * 1024 + 256 * j + 4 * lane); y[j] += (f32x4){bflo(w.x), bfhi(w.x), bflo(w.y), bfhi(w.y)}; } }
;                 ss += (y[j][0] * y[j][0] + y[j][1] * y[j][1]) + (y[j][2] * y[j][2] + y[j][3] * y[j][3]); }
;             const float r = rsqrtf(wave_sum(ss) * (1.0f / 1024.0f) + EPS);
;             if (isx && xd16) { GAS bf16* d16 = (GAS bf16*)xdst + (size_t)row * 1024;
; #pragma unroll
;                 for (int j = 0; j < 4; ++j) { v[j] += pw * gt[j] * ((y[j] * r) * gpo[j]); u32x2 w; w.x = pk2(v[j][0], v[j][1]); w.y = pk2(v[j][2], v[j][3]); __builtin_nontemporal_store(w, (GAS u32x2*)(d16 + 256 * j + 4 * lane));
;                     v[j] = (f32x4){bflo(w.x), bfhi(w.x), bflo(w.y), bfhi(w.y)}; }
;             } else { GAS float* dst = isx ? xdst + (size_t)row * 1024 : cdst + (size_t)(row - MX) * 1024;
; #pragma unroll
;                 for (int j = 0; j < 4; ++j) { v[j] += pw * gt[j] * ((y[j] * r) * gpo[j]); __builtin_nontemporal_store(v[j], (GAS f32x4*)(dst + 256 * j + 4 * lane)); } }
.LBB0_1506:
	v_mul_f32_e32 v130, v141, v141
	v_mul_f32_e32 v131, v139, v139
	v_fmac_f32_e32 v130, v140, v140
	v_fmac_f32_e32 v131, v138, v138
	v_add_f32_e32 v130, v130, v131
	v_mul_f32_e32 v131, v171, v171
	v_mul_f32_e32 v132, v173, v173
	v_fmac_f32_e32 v131, v170, v170
	v_fmac_f32_e32 v132, v172, v172
	v_add_f32_e32 v131, v131, v132
	v_add_f32_e32 v130, v130, v131
	v_mul_f32_e32 v131, v175, v175
	v_mul_f32_e32 v132, v177, v177
	v_fmac_f32_e32 v131, v174, v174
	v_fmac_f32_e32 v132, v176, v176
	v_add_f32_e32 v131, v131, v132
	v_add_f32_e32 v136, v130, v131
	v_pk_mul_f32 v[130:131], v[180:181], v[180:181]
	v_pk_mul_f32 v[132:133], v[178:179], v[178:179]
	s_and_b64 s[0:1], exec, s[0:1]
	v_pk_mov_b32 v[134:135], v[132:133], v[130:131] op_sel:[1,0]
	v_mov_b32_e32 v133, v131
	v_pk_add_f32 v[130:131], v[134:135], v[132:133]
	s_ashr_i32 s11, s10, 31
	v_add_f32_e32 v130, v130, v131
	v_add_f32_e32 v130, v136, v130
	s_nop 1
	v_add_f32_dpp v130, v130, v130 quad_perm:[1,0,3,2] row_mask:0xf bank_mask:0xf
	s_nop 1
	v_add_f32_dpp v130, v130, v130 quad_perm:[2,3,0,1] row_mask:0xf bank_mask:0xf
	s_nop 1
	v_add_f32_dpp v130, v130, v130 row_half_mirror row_mask:0xf bank_mask:0xf
	s_nop 1
	v_add_f32_dpp v130, v130, v130 row_mirror row_mask:0xf bank_mask:0xf
	s_nop 0
	v_readlane_b32 s64, v130, 0
	v_readlane_b32 s65, v130, 16
	v_readlane_b32 s66, v130, 32
	v_readlane_b32 s67, v130, 48
	v_mov_b32_e32 v131, s65
	v_add_f32_e32 v131, s64, v131
	v_mov_b32_e32 v130, s67
	v_add_f32_e32 v130, s66, v130
	v_add_f32_e32 v132, v131, v130
	s_waitcnt lgkmcnt(0)
	s_mov_b64 s[12:13], -1
	s_waitcnt vmcnt(7)
	v_pk_mul_f32 v[188:189], v[102:103], 0.5 op_sel_hi:[1,0]
	s_waitcnt vmcnt(6)
	v_pk_mul_f32 v[186:187], v[106:107], 0.5 op_sel_hi:[1,0]
	s_waitcnt vmcnt(4)
	v_pk_mul_f32 v[184:185], v[110:111], 0.5 op_sel_hi:[1,0]
	v_pk_mul_f32 v[130:131], v[96:97], 0.5 op_sel_hi:[1,0]
	v_fmamk_f32 v132, v132, 0x3a800000, v196
	v_mul_f32_e32 v133, 0x4b800000, v132
	v_cmp_gt_f32_e32 vcc, s27, v132
	s_nop 1
	v_cndmask_b32_e32 v132, v132, v133, vcc
	v_rsq_f32_e32 v134, v132
	v_pk_mul_f32 v[132:133], v[94:95], 0.5 op_sel_hi:[1,0]
	v_mul_f32_e32 v135, 0x45800000, v134
	v_cndmask_b32_e32 v182, v134, v135, vcc
	v_mov_b32_e32 v183, v182
	v_pk_mul_f32 v[134:135], v[138:139], v[182:183] op_sel_hi:[1,0]
	v_pk_mul_f32 v[136:137], v[140:141], v[182:183] op_sel_hi:[1,0]
	v_pk_mul_f32 v[134:135], v[4:5], v[134:135]
	v_pk_mul_f32 v[136:137], v[2:3], v[136:137]
	v_pk_fma_f32 v[100:101], v[130:131], v[134:135], v[100:101]
	v_pk_fma_f32 v[98:99], v[132:133], v[136:137], v[98:99]
	s_mov_b64 vcc, s[0:1]
	s_cbranch_vccz .LBB0_1508
	v_mov_b32_e32 v138, v182
	v_mov_b32_e32 v139, v182
	v_pk_mul_f32 v[132:133], v[172:173], v[138:139]
	v_pk_mul_f32 v[134:135], v[170:171], v[182:183]
	v_pk_mul_f32 v[130:131], v[104:105], 0.5 op_sel_hi:[1,0]
	v_pk_mul_f32 v[132:133], v[8:9], v[132:133]
	v_pk_mul_f32 v[134:135], v[6:7], v[134:135]
	v_pk_mul_f32 v[136:137], v[176:177], v[138:139]
	v_pk_mul_f32 v[140:141], v[174:175], v[182:183]
	v_pk_fma_f32 v[132:133], v[130:131], v[132:133], v[60:61]
	v_pk_fma_f32 v[130:131], v[188:189], v[134:135], v[58:59]
	v_pk_mul_f32 v[134:135], v[108:109], 0.5 op_sel_hi:[1,0]
	v_pk_mul_f32 v[136:137], v[20:21], v[136:137]
	v_pk_mul_f32 v[140:141], v[18:19], v[140:141]
	v_pk_mul_f32 v[138:139], v[180:181], v[138:139]
	v_pk_mul_f32 v[200:201], v[178:179], v[182:183]
	s_lshl_b64 s[0:1], s[4:5], 12
	v_pk_fma_f32 v[136:137], v[134:135], v[136:137], v[56:57]
	v_pk_fma_f32 v[134:135], v[186:187], v[140:141], v[54:55]
	v_pk_mul_f32 v[140:141], v[112:113], 0.5 op_sel_hi:[1,0]
	v_pk_mul_f32 v[138:139], v[24:25], v[138:139]
	v_pk_mul_f32 v[200:201], v[22:23], v[200:201]
	v_lshl_add_u64 v[198:199], v[160:161], 0, s[0:1]
	v_pk_fma_f32 v[140:141], v[140:141], v[138:139], v[48:49]
	v_pk_fma_f32 v[138:139], v[184:185], v[200:201], v[46:47]
	global_store_dwordx4 v[198:199], v[98:101], off nt
	global_store_dwordx4 v[198:199], v[130:133], off offset:1024 nt
	global_store_dwordx4 v[198:199], v[134:137], off offset:2048 nt
	global_store_dwordx4 v[198:199], v[138:141], off offset:3072 nt
	s_lshl_b64 s[2:3], s[10:11], 11
	s_mov_b64 s[12:13], 0

; #define LAS __attribute__((address_space(3)))
; template <bool HASNEXT>
; DI void attn_tile_pipe(const LAS uchar* Kn, int kc0, const LAS uchar* Vb, const bf16x8 (&qf)[4], f32x16 (&O)[4], f32x16 (&S)[2], f32x16 (&Sn)[2], float& m, float& l, int r, int hh, bool force) {
;     constexpr int DVB = 4;
;     const int ksw = r & 15, vsw = (r >> 1) & 7;
;     const LAS uchar* vp = Vb + r * 128;
;     const LAS uchar* kp = Kn + r * 256;
;     bf16x8 kf[4];
;     if (HASNEXT) {
; #pragma unroll
;         for (int s = 0; s < 4; ++s) kf[s] = *(const LAS bf16x8*)(kp + (((kc0 + 2 * s + hh) ^ ksw) * 16)); }
;     bf16x8 vf[DVB];
; #pragma unroll
;     for (int d = 0; d < DVB; ++d) vf[d] = *(const LAS bf16x8*)(vp + d * 32 * 128 + ((hh ^ vsw) * 16));
;     float mx0 = S[0][0], mx1 = S[1][0];
; #pragma unroll
;     for (int i = 1; i < 16; ++i) { mx0 = fmaxf(mx0, S[0][i]); mx1 = fmaxf(mx1, S[1][i]); }
;     float mx = fmaxf(mx0, mx1);
;     if (force || __builtin_amdgcn_ballot_w64(mx > m + 8.0f) != 0ull) {
.LBB0_2028:
	s_mov_b32 s10, s0
	s_add_i32 s0, s0, 0x10000
	s_and_b32 s1, s0, 0x10000
	s_add_i32 s1, s29, s1
	s_nop 7
	v_max_f32_e32 v114, v67, v67
	v_max_f32_e32 v115, v66, v66
	v_max_f32_e32 v114, v115, v114
	v_max3_f32 v115, v82, v83, v84
	s_and_b32 s6, s10, 0x10000
	s_add_i32 s8, s29, s6
	v_add_u32_e32 v106, s8, v198
	v_add_u32_e32 v215, s8, v188
	v_add_u32_e32 v217, v106, v199
	v_add_u32_e32 v219, v106, v201
	v_add_u32_e32 v214, v215, v189
	v_max3_f32 v114, v114, v68, v69
	v_add_u32_e32 v218, v106, v200
	ds_read_b128 v[102:105], v217 offset:32768
	ds_read_b128 v[98:101], v218 offset:32768
	v_add_u32_e32 v220, v106, v202
	ds_read_b128 v[110:113], v219 offset:32768
	ds_read_b128 v[106:109], v220 offset:32768
	ds_read_b128 v[158:161], v214 offset:16384
	ds_read_b128 v[154:157], v214 offset:20480
	ds_read_b128 v[150:153], v214 offset:24576
	ds_read_b128 v[146:149], v214 offset:28672
	v_max3_f32 v115, v115, v85, v86
	v_max3_f32 v114, v114, v70, v71
	v_max3_f32 v115, v115, v87, v88
	v_max3_f32 v114, v114, v72, v73
	v_max3_f32 v115, v115, v89, v90
	v_max3_f32 v114, v114, v74, v75
	v_max3_f32 v115, v115, v91, v92
	v_max3_f32 v114, v114, v76, v77
	s_cmp_eq_u32 s10, 0
	v_max3_f32 v115, v115, v93, v94
	v_max3_f32 v114, v114, v78, v79
	s_cselect_b64 s[6:7], -1, 0
	v_max3_f32 v115, v115, v95, v96
	v_max3_f32 v114, v114, v80, v81
	v_max3_f32 v114, v115, v97, v114
	s_and_b64 vcc, exec, s[6:7]
	s_mov_b64 s[8:9], s[6:7]
	s_cbranch_vccnz .LBB0_2030
	v_cmp_lt_f32_e32 vcc, 0x41000000, v114
	s_cmp_lg_u64 vcc, 0
	s_cselect_b64 s[8:9], -1, 0

; #define LAS __attribute__((address_space(3)))
; #define MFMA32(a, b, c) __builtin_amdgcn_mfma_f32_32x32x16_bf16((a), (b), (c), 0, 0, 0)
; template <bool HASNEXT>
; DI void attn_tile_pipe(const LAS uchar* Kn, int kc0, const LAS uchar* Vb, const bf16x8 (&qf)[4], f32x16 (&O)[4], f32x16 (&S)[2], f32x16 (&Sn)[2], float& m, float& l, int r, int hh, bool force) {
;     ...
;     if (HASNEXT) {
;         __builtin_amdgcn_sched_barrier(0);
;         Sn[0] = MFMA32(kf[0], qf[0], zero16);
; #pragma unroll
;         for (int s = 1; s < 4; ++s) Sn[0] = MFMA32(kf[s], qf[s], Sn[0]);
;         __builtin_amdgcn_sched_barrier(0);
; #pragma unroll
;         for (int s = 0; s < 4; ++s) kf[s] = *(const LAS bf16x8*)(kp + 32 * 256 + (((kc0 + 2 * s + hh) ^ ksw) * 16));
;         __builtin_amdgcn_sched_barrier(0);
;     }
;     ATT_P(0);
;     if (HASNEXT) {
;         __builtin_amdgcn_sched_barrier(0);
;         Sn[1] = MFMA32(kf[0], qf[0], zero16);
; #pragma unroll
;         for (int s = 1; s < 4; ++s) Sn[1] = MFMA32(kf[s], qf[s], Sn[1]);
;     }
; #pragma unroll
;     for (int step = 0; step < 4; ++step) {
;         const bf16x8 pf = __builtin_bit_cast(bf16x8, pw);
;         __builtin_amdgcn_sched_barrier(0);
; #pragma unroll
;         for (int d = 0; d < DVB; ++d) O[d] = MFMA32(vf[d], pf, O[d]);
;         __builtin_amdgcn_sched_barrier(0);
;         if (step < 3) {
; #pragma unroll
;             for (int d = 0; d < DVB; ++d) vf[d] = *(const LAS bf16x8*)(vp + d * 32 * 128 + (((2 * (step + 1) + hh) ^ vsw) * 16));
;             __builtin_amdgcn_sched_barrier(0);
;             ATT_P(step + 1);
;         }
;     }
;     ...
;     l += la0;
.LBB0_2032:
	s_waitcnt lgkmcnt(0)
	v_mfma_f32_32x32x16_bf16 v[114:129], v[102:105], v[134:137], v[238:253]
	v_mfma_f32_32x32x16_bf16 v[114:129], v[98:101], v[130:133], v[114:129]
	v_mfma_f32_32x32x16_bf16 v[114:129], v[110:113], v[142:145], v[114:129]
	v_mfma_f32_32x32x16_bf16 v[114:129], v[106:109], v[138:141], v[114:129]
	s_add_i32 s98, s1, s42
	v_lshl_add_u64 v[254:255], s[4:5], 0, v[182:183]
	s_mov_b32 m0, s98
	s_add_i32 s98, s98, 0x4000
	global_load_lds_dwordx4 v[254:255], off
	v_lshl_add_u64 v[254:255], s[2:3], 0, v[180:181]
	s_mov_b32 m0, s98
	s_nop 0
	global_load_lds_dwordx4 v[254:255], off
	ds_read_b128 v[98:101], v217 offset:40960
	ds_read_b128 v[222:225], v218 offset:40960
	ds_read_b128 v[226:229], v219 offset:40960
	ds_read_b128 v[218:221], v220 offset:40960
	v_exp_f32_e32 v217, v82
	v_exp_f32_e32 v230, v83
	v_exp_f32_e32 v231, v84
	v_exp_f32_e32 v232, v85
	v_exp_f32_e32 v233, v86
	v_exp_f32_e32 v234, v87
	v_exp_f32_e32 v235, v88
	v_exp_f32_e32 v236, v89
	v_cvt_pk_bf16_f32 v82, v217, v230
	v_cvt_pk_bf16_f32 v83, v231, v232
	v_cvt_pk_bf16_f32 v84, v233, v234
	v_cvt_pk_bf16_f32 v85, v235, v236
	s_waitcnt lgkmcnt(0)
	v_mfma_f32_32x32x16_bf16 v[98:113], v[98:101], v[134:137], v[238:253]
	v_mfma_f32_32x32x16_bf16 v[98:113], v[222:225], v[130:133], v[98:113]
	v_mfma_f32_32x32x16_bf16 v[98:113], v[226:229], v[142:145], v[98:113]
	v_mfma_f32_32x32x16_bf16 v[98:113], v[218:221], v[138:141], v[98:113]
	v_mfma_f32_32x32x16_bf16 v[50:65], v[158:161], v[82:85], v[50:65]
	v_mfma_f32_32x32x16_bf16 v[34:49], v[154:157], v[82:85], v[34:49]
	v_mfma_f32_32x32x16_bf16 v[18:33], v[150:153], v[82:85], v[18:33]
	v_mfma_f32_32x32x16_bf16 v[2:17], v[146:149], v[82:85], v[2:17]
	s_add_i32 s98, s1, s43
	v_lshl_add_u64 v[254:255], s[4:5], 0, v[178:179]
	s_mov_b32 m0, s98
	s_add_i32 s98, s98, 0x4000
	global_load_lds_dwordx4 v[254:255], off
	v_lshl_add_u64 v[254:255], s[2:3], 0, v[176:177]
	s_mov_b32 m0, s98
	s_nop 0
	global_load_lds_dwordx4 v[254:255], off
	v_add_u32_e32 v82, v215, v190
	ds_read_b128 v[84:87], v82 offset:16384
	ds_read_b128 v[146:149], v82 offset:20480
	ds_read_b128 v[150:153], v82 offset:24576
	ds_read_b128 v[154:157], v82 offset:28672
	v_exp_f32_e32 v158, v90
	v_exp_f32_e32 v159, v91
	v_exp_f32_e32 v160, v92
	v_exp_f32_e32 v161, v93
	v_exp_f32_e32 v218, v94
	v_exp_f32_e32 v219, v95
	v_exp_f32_e32 v96, v96
	v_exp_f32_e32 v97, v97
	v_cvt_pk_bf16_f32 v88, v158, v159
	v_cvt_pk_bf16_f32 v89, v160, v161
	v_cvt_pk_bf16_f32 v90, v218, v219
	v_cvt_pk_bf16_f32 v91, v96, v97
	s_waitcnt lgkmcnt(0)
	s_nop 0
	v_mfma_f32_32x32x16_bf16 v[50:65], v[84:87], v[88:91], v[50:65]
	v_mfma_f32_32x32x16_bf16 v[34:49], v[146:149], v[88:91], v[34:49]
	v_mfma_f32_32x32x16_bf16 v[18:33], v[150:153], v[88:91], v[18:33]
	v_mfma_f32_32x32x16_bf16 v[2:17], v[154:157], v[88:91], v[2:17]
	s_add_i32 s98, s1, s44
	v_lshl_add_u64 v[254:255], s[4:5], 0, v[174:175]
	s_mov_b32 m0, s98
	s_add_i32 s98, s98, 0x4000
	global_load_lds_dwordx4 v[254:255], off
	v_lshl_add_u64 v[254:255], s[2:3], 0, v[172:173]
	s_mov_b32 m0, s98
	s_nop 0
	global_load_lds_dwordx4 v[254:255], off
	v_add_u32_e32 v83, v215, v191
	ds_read_b128 v[84:87], v83 offset:16384
	ds_read_b128 v[88:91], v83 offset:20480
	ds_read_b128 v[92:95], v83 offset:24576
	ds_read_b128 v[146:149], v83 offset:28672
	v_exp_f32_e32 v150, v66
	v_exp_f32_e32 v151, v67
	v_exp_f32_e32 v152, v68
	v_exp_f32_e32 v153, v69
	v_exp_f32_e32 v154, v70
	v_exp_f32_e32 v155, v71
	v_exp_f32_e32 v156, v72
	v_exp_f32_e32 v157, v73
	v_cvt_pk_bf16_f32 v66, v150, v151
	v_cvt_pk_bf16_f32 v67, v152, v153
	v_cvt_pk_bf16_f32 v68, v154, v155
	v_cvt_pk_bf16_f32 v69, v156, v157
	s_waitcnt lgkmcnt(0)
	s_nop 0
	v_mfma_f32_32x32x16_bf16 v[50:65], v[84:87], v[66:69], v[50:65]
	v_mfma_f32_32x32x16_bf16 v[34:49], v[88:91], v[66:69], v[34:49]
	v_mfma_f32_32x32x16_bf16 v[18:33], v[92:95], v[66:69], v[18:33]
	v_mfma_f32_32x32x16_bf16 v[2:17], v[146:149], v[66:69], v[2:17]
	s_add_i32 s98, s1, s45
	v_lshl_add_u64 v[254:255], s[4:5], 0, v[170:171]
	s_mov_b32 m0, s98
	s_add_i32 s98, s98, 0x4000
	global_load_lds_dwordx4 v[254:255], off
	v_lshl_add_u64 v[254:255], s[2:3], 0, v[168:169]
	s_mov_b32 m0, s98
	s_nop 0
	global_load_lds_dwordx4 v[254:255], off
	v_add_u32_e32 v84, v215, v192
	ds_read_b128 v[66:69], v84 offset:16384
	ds_read_b128 v[70:73], v84 offset:20480
	ds_read_b128 v[86:89], v84 offset:24576
	ds_read_b128 v[90:93], v84 offset:28672
	v_exp_f32_e32 v85, v74
	v_exp_f32_e32 v94, v75
	v_exp_f32_e32 v95, v76
	v_exp_f32_e32 v146, v77
	v_exp_f32_e32 v78, v78
	v_exp_f32_e32 v79, v79
	v_exp_f32_e32 v80, v80
	v_exp_f32_e32 v81, v81
	v_cvt_pk_bf16_f32 v74, v85, v94
	v_cvt_pk_bf16_f32 v75, v95, v146
	v_cvt_pk_bf16_f32 v76, v78, v79
	v_cvt_pk_bf16_f32 v77, v80, v81
	s_waitcnt lgkmcnt(0)
	s_nop 0
	v_mfma_f32_32x32x16_bf16 v[50:65], v[66:69], v[74:77], v[50:65]
	v_mfma_f32_32x32x16_bf16 v[34:49], v[70:73], v[74:77], v[34:49]
	v_mfma_f32_32x32x16_bf16 v[18:33], v[86:89], v[74:77], v[18:33]
	v_mfma_f32_32x32x16_bf16 v[2:17], v[90:93], v[74:77], v[2:17]
	v_add_f32_e32 v66, 0, v217
	v_add_f32_e32 v66, v230, v66
	v_add_f32_e32 v66, v231, v66
	v_add_f32_e32 v66, v232, v66
	v_add_f32_e32 v66, v233, v66
	v_add_f32_e32 v66, v234, v66
	v_add_f32_e32 v66, v235, v66
	v_add_f32_e32 v66, v236, v66
	v_add_f32_e32 v66, v158, v66
	v_add_f32_e32 v66, v159, v66
	v_add_f32_e32 v66, v160, v66
	v_add_f32_e32 v66, v161, v66
	v_add_f32_e32 v66, v218, v66
	v_add_f32_e32 v66, v219, v66
	v_add_f32_e32 v66, v96, v66
	v_add_f32_e32 v66, v97, v66
	v_add_f32_e32 v66, v150, v66
	v_add_f32_e32 v66, v151, v66
	v_add_f32_e32 v66, v152, v66
	v_add_f32_e32 v66, v153, v66
	v_add_f32_e32 v66, v154, v66
	v_add_f32_e32 v66, v155, v66
	v_add_f32_e32 v66, v156, v66
	v_add_f32_e32 v66, v157, v66
	v_add_f32_e32 v66, v85, v66
	v_add_f32_e32 v66, v94, v66
	v_add_f32_e32 v66, v95, v66
	v_add_f32_e32 v66, v146, v66
	v_add_f32_e32 v66, v78, v66
	v_max_f32_e32 v85, v99, v99
	v_max_f32_e32 v86, v98, v98
	v_add_f32_e32 v66, v79, v66
	v_max_f32_e32 v85, v86, v85
	v_add_f32_e32 v66, v80, v66
	v_max3_f32 v86, v114, v115, v116
	v_max3_f32 v85, v85, v100, v101
	v_add_f32_e32 v66, v81, v66
	v_max3_f32 v86, v86, v117, v118
	v_max3_f32 v85, v85, v102, v103
	v_add_f32_e32 v146, v213, v66
	ds_read_b128 v[78:81], v214 offset:49152
	ds_read_b128 v[74:77], v214 offset:53248
	ds_read_b128 v[70:73], v214 offset:57344
	ds_read_b128 v[66:69], v214 offset:61440
	v_max3_f32 v86, v86, v119, v120
	v_max3_f32 v85, v85, v104, v105
	v_max3_f32 v86, v86, v121, v122
	v_max3_f32 v85, v85, v106, v107
	v_max3_f32 v86, v86, v123, v124
	v_max3_f32 v85, v85, v108, v109
	v_max3_f32 v86, v86, v125, v126
	v_max3_f32 v85, v85, v110, v111
	v_max3_f32 v86, v86, v127, v128
	v_max3_f32 v85, v85, v112, v113
	v_max3_f32 v85, v86, v129, v85
	v_cmp_lt_f32_e32 vcc, 0x41000000, v85
	s_cbranch_vccz .LBB0_2027
; template <int DVB, bool MASK, bool KW16>
; DI void attn_tile(const LAS uchar* Kb, int kc0, const LAS uchar* Vb, const bf16x8 (&qf)[4], f32x16 (&O)[DVB], float& m, f32x16& negm, float& l, int r, int hh, int tq, int tk0, bool force) {
;     ...
;     if (force || __builtin_amdgcn_ballot_w64(mx > 8.0f) != 0ull) {
;         mx = fmaxf(mx, __shfl_xor(mx, 32));
;         const float delta = force ? mx : fmaxf(mx, 0.f);
;         const float alpha = __builtin_amdgcn_exp2f(-delta);
;         m += delta; l *= alpha;
; #pragma unroll
;         for (int i = 0; i < 16; ++i) negm[i] = -m;
; #pragma unroll
;         for (int d = 0; d < DVB; ++d) O[d] *= alpha;
; #pragma unroll
;         for (int kb = 0; kb < 2; ++kb)
; #pragma unroll
;             for (int i = 0; i < 16; ++i) S[kb][i] -= delta;
;     }
	ds_bpermute_b32 v86, v165, v85
	s_waitcnt lgkmcnt(0)
	v_max3_f32 v85, v85, v86, 0
	v_sub_f32_e32 v86, 0, v85
	v_exp_f32_e32 v86, v86
	v_add_f32_e32 v212, v212, v85
	v_sub_f32_e32 v238, v238, v85
	v_mov_b32_e32 v239, v238
	v_mov_b32_e32 v240, v238
	v_mov_b32_e32 v241, v238
	v_mov_b32_e32 v242, v238
	v_mov_b32_e32 v243, v238
	v_mov_b32_e32 v244, v238
	v_mov_b32_e32 v245, v238
	v_mov_b32_e32 v246, v238
	v_mov_b32_e32 v247, v238
	v_mov_b32_e32 v248, v238
	v_mov_b32_e32 v249, v238
	v_mov_b32_e32 v250, v238
	v_mov_b32_e32 v251, v238
	v_mov_b32_e32 v252, v238
	v_mov_b32_e32 v253, v238
	v_sub_f32_e32 v114, v114, v85
	v_sub_f32_e32 v115, v115, v85
	v_sub_f32_e32 v116, v116, v85
	v_sub_f32_e32 v117, v117, v85
	v_sub_f32_e32 v118, v118, v85
	v_sub_f32_e32 v119, v119, v85
	v_sub_f32_e32 v120, v120, v85
	v_sub_f32_e32 v121, v121, v85
	v_sub_f32_e32 v122, v122, v85
	v_sub_f32_e32 v123, v123, v85
	v_sub_f32_e32 v124, v124, v85
	v_sub_f32_e32 v125, v125, v85
	v_sub_f32_e32 v126, v126, v85
	v_sub_f32_e32 v127, v127, v85
	v_sub_f32_e32 v128, v128, v85
	v_sub_f32_e32 v129, v129, v85
	v_sub_f32_e32 v98, v98, v85
	v_sub_f32_e32 v99, v99, v85
	v_sub_f32_e32 v100, v100, v85
	v_sub_f32_e32 v101, v101, v85
	v_sub_f32_e32 v102, v102, v85
	v_sub_f32_e32 v103, v103, v85
	v_sub_f32_e32 v104, v104, v85
	v_sub_f32_e32 v105, v105, v85
	v_sub_f32_e32 v106, v106, v85
	v_sub_f32_e32 v107, v107, v85
	v_sub_f32_e32 v108, v108, v85
	v_sub_f32_e32 v109, v109, v85
	v_sub_f32_e32 v110, v110, v85
	v_sub_f32_e32 v111, v111, v85
	v_sub_f32_e32 v112, v112, v85
	v_sub_f32_e32 v113, v113, v85
	v_mul_f32_e32 v146, v146, v86
	v_pk_mul_f32 v[64:65], v[64:65], v[86:87] op_sel_hi:[1,0]
	v_pk_mul_f32 v[62:63], v[62:63], v[86:87] op_sel_hi:[1,0]
	v_pk_mul_f32 v[60:61], v[60:61], v[86:87] op_sel_hi:[1,0]
	v_pk_mul_f32 v[58:59], v[58:59], v[86:87] op_sel_hi:[1,0]
	v_pk_mul_f32 v[56:57], v[56:57], v[86:87] op_sel_hi:[1,0]
	v_pk_mul_f32 v[54:55], v[54:55], v[86:87] op_sel_hi:[1,0]
	v_pk_mul_f32 v[52:53], v[52:53], v[86:87] op_sel_hi:[1,0]
	v_pk_mul_f32 v[50:51], v[50:51], v[86:87] op_sel_hi:[1,0]
	v_pk_mul_f32 v[48:49], v[48:49], v[86:87] op_sel_hi:[1,0]
	v_pk_mul_f32 v[46:47], v[46:47], v[86:87] op_sel_hi:[1,0]
	v_pk_mul_f32 v[44:45], v[44:45], v[86:87] op_sel_hi:[1,0]
	v_pk_mul_f32 v[42:43], v[42:43], v[86:87] op_sel_hi:[1,0]
	v_pk_mul_f32 v[40:41], v[40:41], v[86:87] op_sel_hi:[1,0]
	v_pk_mul_f32 v[38:39], v[38:39], v[86:87] op_sel_hi:[1,0]
	v_pk_mul_f32 v[36:37], v[36:37], v[86:87] op_sel_hi:[1,0]
	v_pk_mul_f32 v[34:35], v[34:35], v[86:87] op_sel_hi:[1,0]
	v_pk_mul_f32 v[32:33], v[32:33], v[86:87] op_sel_hi:[1,0]
	v_pk_mul_f32 v[30:31], v[30:31], v[86:87] op_sel_hi:[1,0]
	v_pk_mul_f32 v[28:29], v[28:29], v[86:87] op_sel_hi:[1,0]
	v_pk_mul_f32 v[26:27], v[26:27], v[86:87] op_sel_hi:[1,0]
	v_pk_mul_f32 v[24:25], v[24:25], v[86:87] op_sel_hi:[1,0]
	v_pk_mul_f32 v[22:23], v[22:23], v[86:87] op_sel_hi:[1,0]
	v_pk_mul_f32 v[20:21], v[20:21], v[86:87] op_sel_hi:[1,0]
	v_pk_mul_f32 v[18:19], v[18:19], v[86:87] op_sel_hi:[1,0]
	v_pk_mul_f32 v[16:17], v[16:17], v[86:87] op_sel_hi:[1,0]
	v_pk_mul_f32 v[14:15], v[14:15], v[86:87] op_sel_hi:[1,0]
	v_pk_mul_f32 v[12:13], v[12:13], v[86:87] op_sel_hi:[1,0]
	v_pk_mul_f32 v[10:11], v[10:11], v[86:87] op_sel_hi:[1,0]
	v_pk_mul_f32 v[8:9], v[8:9], v[86:87] op_sel_hi:[1,0]
	v_pk_mul_f32 v[6:7], v[6:7], v[86:87] op_sel_hi:[1,0]
	v_pk_mul_f32 v[4:5], v[4:5], v[86:87] op_sel_hi:[1,0]
	v_pk_mul_f32 v[2:3], v[2:3], v[86:87] op_sel_hi:[1,0]
	s_branch .LBB0_2027

; #define GAS __attribute__((address_space(1)))
; DI unsigned pk2(float lo, float hi) { f32x2_t v = {lo, hi}; bf16x2_t b = __builtin_convertvector(v, bf16x2_t); return __builtin_bit_cast(unsigned, b); }
; DI float wave_sum(float v) {
; #pragma unroll
;     for (int o = 1; o < 64; o <<= 1) v += __shfl_xor(v, o);
;     return v;
; }
; DI void phase_e(const Ctx& C, int nslab, int has_post, int pl, int ps, float pw, int has_pre, int ql, int qs, int nrows,
;                 const GAS float* xsrc, const GAS float* csrc, GAS float* xdst, GAS float* cdst, bool xs16, bool xd16) {
;     ...
;         if (has_pre) {
;             float ss = 0.f;
; #pragma unroll
;             for (int j = 0; j < 4; ++j) ss += (v[j][0] * v[j][0] + v[j][1] * v[j][1]) + (v[j][2] * v[j][2] + v[j][3] * v[j][3]);
;             const float r = rsqrtf(wave_sum(ss) * (1.0f / 1024.0f) + EPS);
; #pragma unroll
;             for (int j = 0; j < 4; ++j) { const f32x4 h = ((v[j] * r) * gpr[j]) * (1.0f + sc[j]) + sh[j];
;                 u32x2 w; w.x = pk2(h[0], h[1]); w.y = pk2(h[2], h[3]); *(GAS u32x2*)(H + (size_t)row * 1024 + 256 * j + 4 * lane) = w; }
;         }
.LBB0_2209:
	v_pk_mul_f32 v[54:55], v[132:133], v[132:133]
	v_pk_mul_f32 v[56:57], v[130:131], v[130:131]
	v_pk_mul_f32 v[50:51], v[136:137], v[136:137]
	v_pk_mul_f32 v[52:53], v[134:135], v[134:135]
	v_pk_mov_b32 v[58:59], v[56:57], v[54:55] op_sel:[1,0]
	v_mov_b32_e32 v57, v55
	v_pk_add_f32 v[54:55], v[58:59], v[56:57]
	v_pk_mov_b32 v[56:57], v[52:53], v[50:51] op_sel:[1,0]
	v_mov_b32_e32 v53, v51
	v_pk_add_f32 v[50:51], v[56:57], v[52:53]
	v_pk_add_f32 v[54:55], v[54:55], v[54:55] op_sel_hi:[0,1]
	v_pk_add_f32 v[50:51], v[50:51], v[50:51] op_sel_hi:[0,1]
	v_mul_f32_e32 v50, v138, v138
	v_pk_fma_f32 v[52:53], v[138:139], v[138:139], v[50:51] op_sel_hi:[1,1,0]
	v_mul_f32_e32 v50, v140, v140
	v_pk_fma_f32 v[56:57], v[140:141], v[140:141], v[50:51] op_sel_hi:[1,1,0]
	v_mul_f32_e32 v52, v142, v142
	v_mul_f32_e32 v56, v143, v143
	v_mul_f32_e32 v54, v144, v144
	v_mul_f32_e32 v50, v145, v145
	v_pk_add_f32 v[52:53], v[52:53], v[56:57]
	v_pk_add_f32 v[50:51], v[54:55], v[50:51]
	s_waitcnt vmcnt(10)
	v_pk_add_f32 v[54:55], v[70:71], 1.0 op_sel_hi:[1,0]
	v_pk_add_f32 v[50:51], v[52:53], v[50:51]
	v_pk_add_f32 v[52:53], v[72:73], 1.0 op_sel_hi:[1,0]
	v_add_f32_e32 v50, v50, v51
	s_nop 1
	v_add_f32_dpp v50, v50, v50 quad_perm:[1,0,3,2] row_mask:0xf bank_mask:0xf
	s_nop 1
	v_add_f32_dpp v50, v50, v50 quad_perm:[2,3,0,1] row_mask:0xf bank_mask:0xf
	s_nop 1
	v_add_f32_dpp v50, v50, v50 row_half_mirror row_mask:0xf bank_mask:0xf
	s_nop 1
	v_add_f32_dpp v50, v50, v50 row_mirror row_mask:0xf bank_mask:0xf
	s_nop 0
	v_readlane_b32 s64, v50, 0
	v_readlane_b32 s65, v50, 16
	v_readlane_b32 s66, v50, 32
	v_readlane_b32 s67, v50, 48
	v_mov_b32_e32 v51, s65
	v_add_f32_e32 v51, s64, v51
	v_mov_b32_e32 v50, s67
	v_add_f32_e32 v50, s66, v50
	v_add_f32_e32 v50, v51, v50
	s_waitcnt lgkmcnt(0)
	s_add_i32 s16, s16, 8
	s_cmp_lt_i32 s16, s17
	v_fmamk_f32 v50, v50, 0x3a800000, v197
	v_mul_f32_e32 v51, 0x4b800000, v50
	v_cmp_gt_f32_e32 vcc, s22, v50
	s_nop 1
	v_cndmask_b32_e32 v50, v50, v51, vcc
	v_rsq_f32_e32 v56, v50
	v_lshl_add_u64 v[50:51], v[162:163], 0, s[8:9]
	v_mul_f32_e32 v57, 0x45800000, v56
	v_cndmask_b32_e32 v56, v56, v57, vcc
	v_pk_mul_f32 v[58:59], v[132:133], v[56:57] op_sel_hi:[1,0]
	v_pk_mul_f32 v[60:61], v[130:131], v[56:57] op_sel_hi:[1,0]
	v_pk_mul_f32 v[58:59], v[12:13], v[58:59]
	v_pk_mul_f32 v[60:61], v[10:11], v[60:61]
	s_waitcnt vmcnt(9)
	v_pk_fma_f32 v[52:53], v[52:53], v[58:59], v[76:77]
	v_pk_fma_f32 v[54:55], v[54:55], v[60:61], v[74:75]
	v_pk_mul_f32 v[62:63], v[136:137], v[56:57] op_sel_hi:[1,0]
	v_pk_mul_f32 v[64:65], v[134:135], v[56:57] op_sel_hi:[1,0]
	v_cvt_pk_bf16_f32 v54, v54, v55
	v_cvt_pk_bf16_f32 v55, v52, v53
	v_pk_mul_f32 v[64:65], v[14:15], v[64:65]
	global_store_dwordx2 v[50:51], v[54:55], off
	v_pk_mul_f32 v[52:53], v[16:17], v[62:63]
	s_waitcnt vmcnt(6)
	v_pk_add_f32 v[54:55], v[80:81], 1.0 op_sel_hi:[1,0]
	v_pk_add_f32 v[58:59], v[78:79], 1.0 op_sel_hi:[1,0]
	v_pk_fma_f32 v[52:53], v[54:55], v[52:53], v[84:85]
	v_pk_fma_f32 v[54:55], v[58:59], v[64:65], v[82:83]
	s_waitcnt vmcnt(4)
	v_pk_add_f32 v[58:59], v[88:89], 1.0 op_sel_hi:[1,0]
	v_cvt_pk_bf16_f32 v54, v54, v55
	v_cvt_pk_bf16_f32 v55, v52, v53
	global_store_dwordx2 v[50:51], v[54:55], off offset:512
	v_pk_mul_f32 v[52:53], v[140:141], v[56:57] op_sel_hi:[1,0]
	v_pk_mul_f32 v[54:55], v[138:139], v[56:57] op_sel_hi:[1,0]
	v_pk_mul_f32 v[52:53], v[28:29], v[52:53]
	v_pk_mul_f32 v[54:55], v[26:27], v[54:55]
	v_pk_add_f32 v[60:61], v[86:87], 1.0 op_sel_hi:[1,0]
	s_waitcnt vmcnt(3)
	v_pk_fma_f32 v[52:53], v[58:59], v[52:53], v[96:97]
	v_pk_fma_f32 v[54:55], v[60:61], v[54:55], v[94:95]
	v_pk_add_f32 v[58:59], v[66:67], 1.0 op_sel_hi:[1,0]
	v_cvt_pk_bf16_f32 v54, v54, v55
	v_cvt_pk_bf16_f32 v55, v52, v53
	global_store_dwordx2 v[50:51], v[54:55], off offset:1024
	v_pk_mul_f32 v[52:53], v[144:145], v[56:57] op_sel_hi:[1,0]
	v_pk_mul_f32 v[54:55], v[142:143], v[56:57] op_sel_hi:[1,0]
	v_pk_mul_f32 v[52:53], v[32:33], v[52:53]
	v_pk_mul_f32 v[54:55], v[30:31], v[54:55]
	v_pk_add_f32 v[56:57], v[68:69], 1.0 op_sel_hi:[1,0]
	s_waitcnt vmcnt(3)
	v_pk_fma_f32 v[54:55], v[58:59], v[54:55], v[90:91]
	v_pk_fma_f32 v[52:53], v[56:57], v[52:53], v[92:93]
	v_cvt_pk_bf16_f32 v54, v54, v55
	v_cvt_pk_bf16_f32 v55, v52, v53
	global_store_dwordx2 v[50:51], v[54:55], off offset:1536
	s_mov_b64 vcc, s[98:99]
	s_cbranch_vccz .Leload_skip_3
	s_waitcnt vmcnt(8)
	v_lshlrev_b32_e32 v114, 16, v116
	v_and_b32_e32 v115, 0xffff0000, v116
	v_lshlrev_b32_e32 v116, 16, v117
	v_and_b32_e32 v117, 0xffff0000, v117
	v_lshlrev_b32_e32 v118, 16, v120
	v_and_b32_e32 v119, 0xffff0000, v120
	v_lshlrev_b32_e32 v120, 16, v121
	v_and_b32_e32 v121, 0xffff0000, v121
	v_lshlrev_b32_e32 v122, 16, v124
	v_and_b32_e32 v123, 0xffff0000, v124
	v_lshlrev_b32_e32 v124, 16, v125
	v_and_b32_e32 v125, 0xffff0000, v125
	v_lshlrev_b32_e32 v126, 16, v128
	v_and_b32_e32 v127, 0xffff0000, v128
	v_lshlrev_b32_e32 v128, 16, v129
	v_and_b32_e32 v129, 0xffff0000, v129

; #define GAS __attribute__((address_space(1)))
; DI unsigned pk2(float lo, float hi) { f32x2_t v = {lo, hi}; bf16x2_t b = __builtin_convertvector(v, bf16x2_t); return __builtin_bit_cast(unsigned, b); }
; DI float bflo(unsigned w) { return __uint_as_float(w << 16); }
; DI float bfhi(unsigned w) { return __uint_as_float(w & 0xffff0000u); }
; DI float wave_sum(float v) {
; #pragma unroll
;     for (int o = 1; o < 64; o <<= 1) v += __shfl_xor(v, o);
;     return v;
; }
; DI void phase_e(const Ctx& C, int nslab, int has_post, int pl, int ps, float pw, int has_pre, int ql, int qs, int nrows,
;                 const GAS float* xsrc, const GAS float* csrc, GAS float* xdst, GAS float* cdst, bool xs16, bool xd16) {
;     ...
;         if (has_post) {
;             f32x4 y[4]; float ss = 0.f;
; #pragma unroll
;             for (int j = 0; j < 4; ++j) {
;                 if (isx || nslab == 0) { y[j] = (f32x4){bflo(yw[j].x), bfhi(yw[j].x), bflo(yw[j].y), bfhi(yw[j].y)}; }
;                 else { y[j] = (f32x4){0.f, 0.f, 0.f, 0.f};
;                     for (int s = 0; s < nslab; ++s) { const u32x2 w = *(const GAS u32x2*)(YS + ((size_t)s * MC + (row - MX)) * 1024 + 256 * j + 4 * lane); y[j] += (f32x4){bflo(w.x), bfhi(w.x), bflo(w.y), bfhi(w.y)}; } }
;                 ss += (y[j][0] * y[j][0] + y[j][1] * y[j][1]) + (y[j][2] * y[j][2] + y[j][3] * y[j][3]); }
;             const float r = rsqrtf(wave_sum(ss) * (1.0f / 1024.0f) + EPS);
;             if (isx && xd16) { GAS bf16* d16 = (GAS bf16*)xdst + (size_t)row * 1024;
; #pragma unroll
;                 for (int j = 0; j < 4; ++j) { v[j] += pw * gt[j] * ((y[j] * r) * gpo[j]); u32x2 w; w.x = pk2(v[j][0], v[j][1]); w.y = pk2(v[j][2], v[j][3]); __builtin_nontemporal_store(w, (GAS u32x2*)(d16 + 256 * j + 4 * lane));
;                     v[j] = (f32x4){bflo(w.x), bfhi(w.x), bflo(w.y), bfhi(w.y)}; }
;             } else { GAS float* dst = isx ? xdst + (size_t)row * 1024 : cdst + (size_t)(row - MX) * 1024;
; #pragma unroll
;                 for (int j = 0; j < 4; ++j) { v[j] += pw * gt[j] * ((y[j] * r) * gpo[j]); __builtin_nontemporal_store(v[j], (GAS f32x4*)(dst + 256 * j + 4 * lane)); } }
.LBB0_2218:
	v_and_b32_e32 v189, 0xffff0000, v137
	v_and_b32_e32 v188, 0xffff0000, v136
	v_and_b32_e32 v185, 0xffff0000, v135
	v_and_b32_e32 v184, 0xffff0000, v134
	v_lshlrev_b32_e32 v187, 16, v137
	v_lshlrev_b32_e32 v186, 16, v136
	v_pk_mul_f32 v[136:137], v[188:189], v[188:189]
	v_lshlrev_b32_e32 v183, 16, v135
	v_lshlrev_b32_e32 v182, 16, v134
	v_pk_mul_f32 v[134:135], v[184:185], v[184:185]
	v_lshlrev_b32_e32 v178, 16, v132
	v_and_b32_e32 v179, 0xffff0000, v132
	v_lshlrev_b32_e32 v180, 16, v133
	v_lshlrev_b32_e32 v174, 16, v130
	v_pk_fma_f32 v[136:137], v[186:187], v[186:187], v[136:137]
	v_pk_fma_f32 v[134:135], v[182:183], v[182:183], v[134:135]
	v_mul_f32_e32 v139, v178, v178
	v_mul_f32_e32 v141, v179, v179
	v_and_b32_e32 v181, 0xffff0000, v133
	v_mul_f32_e32 v132, v180, v180
	v_mov_b32_e32 v138, v174
	v_mov_b32_e32 v140, v174
	v_pk_add_f32 v[136:137], v[136:137], v[136:137] op_sel_hi:[0,1]
	v_pk_add_f32 v[134:135], v[134:135], v[134:135] op_sel_hi:[0,1]
	v_pk_fma_f32 v[132:133], v[180:181], v[180:181], v[132:133] op_sel_hi:[1,1,0]
	v_and_b32_e32 v175, 0xffff0000, v130
	v_lshlrev_b32_e32 v176, 16, v131
	v_and_b32_e32 v177, 0xffff0000, v131
	v_pk_add_f32 v[138:139], v[138:139], v[140:141]
	v_mul_f32_e32 v132, v175, v175
	v_mul_f32_e32 v134, v176, v176
	v_mul_f32_e32 v136, v177, v177
	v_mul_f32_e32 v130, v174, v174
	v_mov_b32_e32 v131, v139
	v_pk_add_f32 v[130:131], v[130:131], v[132:133]
	v_pk_add_f32 v[132:133], v[134:135], v[136:137]
	s_ashr_i32 s7, s6, 31
	v_pk_add_f32 v[130:131], v[130:131], v[132:133]
	s_cmpk_gt_i32 s6, 0x7fff
	v_add_f32_e32 v130, v130, v131
	s_nop 1
	v_add_f32_dpp v130, v130, v130 quad_perm:[1,0,3,2] row_mask:0xf bank_mask:0xf
	s_nop 1
	v_add_f32_dpp v130, v130, v130 quad_perm:[2,3,0,1] row_mask:0xf bank_mask:0xf
	s_nop 1
	v_add_f32_dpp v130, v130, v130 row_half_mirror row_mask:0xf bank_mask:0xf
	s_nop 1
	v_add_f32_dpp v130, v130, v130 row_mirror row_mask:0xf bank_mask:0xf
	s_nop 0
	v_readlane_b32 s64, v130, 0
	v_readlane_b32 s65, v130, 16
	v_readlane_b32 s66, v130, 32
	v_readlane_b32 s67, v130, 48
	v_mov_b32_e32 v131, s65
	v_add_f32_e32 v131, s64, v131
	v_mov_b32_e32 v130, s67
	v_add_f32_e32 v130, s66, v130
	v_add_f32_e32 v130, v131, v130
	s_waitcnt lgkmcnt(0)
	s_mov_b64 s[10:11], -1
	v_fmamk_f32 v130, v130, 0x3a800000, v197
	v_mul_f32_e32 v131, 0x4b800000, v130
	v_cmp_gt_f32_e32 vcc, s22, v130
	s_nop 1
	v_cndmask_b32_e32 v130, v130, v131, vcc
	v_rsq_f32_e32 v130, v130
	s_nop 0
	v_mul_f32_e32 v131, 0x45800000, v130
	v_cndmask_b32_e32 v190, v130, v131, vcc
	s_cbranch_scc0 .LBB0_2220
	v_mov_b32_e32 v130, v187
	v_mov_b32_e32 v131, v189
	v_mov_b32_e32 v132, v186
	v_mov_b32_e32 v133, v188
	v_pk_mul_f32 v[130:131], v[130:131], v[190:191] op_sel_hi:[1,0]
	v_pk_mul_f32 v[132:133], v[132:133], v[190:191] op_sel_hi:[1,0]
	v_pk_mul_f32 v[130:131], v[4:5], v[130:131]
	v_pk_mul_f32 v[134:135], v[2:3], v[132:133]
	s_waitcnt vmcnt(11)
	v_pk_fma_f32 v[132:133], v[100:101], v[130:131], v[64:65]
	v_pk_fma_f32 v[130:131], v[98:99], v[134:135], v[62:63]
	v_mov_b32_e32 v134, v183
	v_mov_b32_e32 v135, v185
	v_mov_b32_e32 v136, v182
	v_mov_b32_e32 v137, v184
	v_pk_mul_f32 v[134:135], v[134:135], v[190:191] op_sel_hi:[1,0]
	v_pk_mul_f32 v[136:137], v[136:137], v[190:191] op_sel_hi:[1,0]
	v_pk_mul_f32 v[134:135], v[8:9], v[134:135]
	v_pk_mul_f32 v[138:139], v[6:7], v[136:137]
	s_add_i32 s0, s6, 0xffff8000
	s_waitcnt vmcnt(7)
	v_pk_fma_f32 v[136:137], v[104:105], v[134:135], v[60:61]
	v_pk_fma_f32 v[134:135], v[102:103], v[138:139], v[58:59]
	v_pk_mul_f32 v[138:139], v[178:179], v[190:191] op_sel_hi:[1,0]
	v_pk_mul_f32 v[140:141], v[180:181], v[190:191] op_sel_hi:[1,0]
	v_pk_mul_f32 v[142:143], v[176:177], v[190:191] op_sel_hi:[1,0]
	v_pk_mul_f32 v[144:145], v[174:175], v[190:191] op_sel_hi:[1,0]
	s_lshl_b64 s[8:9], s[0:1], 12
	v_pk_mul_f32 v[138:139], v[18:19], v[138:139]
	v_pk_mul_f32 v[140:141], v[20:21], v[140:141]
	v_pk_mul_f32 v[200:201], v[22:23], v[144:145]
	v_pk_mul_f32 v[142:143], v[24:25], v[142:143]
	v_lshl_add_u64 v[198:199], v[164:165], 0, s[8:9]
	s_waitcnt vmcnt(6)
	v_pk_fma_f32 v[140:141], v[108:109], v[140:141], v[56:57]
	v_pk_fma_f32 v[138:139], v[106:107], v[138:139], v[54:55]
	s_waitcnt vmcnt(4)
	v_pk_fma_f32 v[144:145], v[112:113], v[142:143], v[52:53]
	v_pk_fma_f32 v[142:143], v[110:111], v[200:201], v[50:51]
	global_store_dwordx4 v[198:199], v[130:133], off nt
	global_store_dwordx4 v[198:199], v[134:137], off offset:1024 nt
	global_store_dwordx4 v[198:199], v[138:141], off offset:2048 nt
	global_store_dwordx4 v[198:199], v[142:145], off offset:3072 nt
	s_lshl_b64 s[8:9], s[6:7], 11
	s_mov_b64 s[10:11], 0

; #define GAS __attribute__((address_space(1)))
; DI unsigned pk2(float lo, float hi) { f32x2_t v = {lo, hi}; bf16x2_t b = __builtin_convertvector(v, bf16x2_t); return __builtin_bit_cast(unsigned, b); }
; DI float bflo(unsigned w) { return __uint_as_float(w << 16); }
; DI float bfhi(unsigned w) { return __uint_as_float(w & 0xffff0000u); }
; DI float wave_sum(float v) {
; #pragma unroll
;     for (int o = 1; o < 64; o <<= 1) v += __shfl_xor(v, o);
;     return v;
; }
; DI void phase_e(const Ctx& C, int nslab, int has_post, int pl, int ps, float pw, int has_pre, int ql, int qs, int nrows,
;                 const GAS float* xsrc, const GAS float* csrc, GAS float* xdst, GAS float* cdst, bool xs16, bool xd16) {
;     ...
;             f32x4 y[4]; float ss = 0.f;
; #pragma unroll
;             for (int j = 0; j < 4; ++j) {
;                 if (isx || nslab == 0) { y[j] = (f32x4){bflo(yw[j].x), bfhi(yw[j].x), bflo(yw[j].y), bfhi(yw[j].y)}; }
;                 else { y[j] = (f32x4){0.f, 0.f, 0.f, 0.f};
;                     for (int s = 0; s < nslab; ++s) { const u32x2 w = *(const GAS u32x2*)(YS + ((size_t)s * MC + (row - MX)) * 1024 + 256 * j + 4 * lane); y[j] += (f32x4){bflo(w.x), bfhi(w.x), bflo(w.y), bfhi(w.y)}; } }
;                 ss += (y[j][0] * y[j][0] + y[j][1] * y[j][1]) + (y[j][2] * y[j][2] + y[j][3] * y[j][3]); }
;             const float r = rsqrtf(wave_sum(ss) * (1.0f / 1024.0f) + EPS);
;             if (isx && xd16) { GAS bf16* d16 = (GAS bf16*)xdst + (size_t)row * 1024;
; #pragma unroll
;                 for (int j = 0; j < 4; ++j) { v[j] += pw * gt[j] * ((y[j] * r) * gpo[j]); u32x2 w; w.x = pk2(v[j][0], v[j][1]); w.y = pk2(v[j][2], v[j][3]); __builtin_nontemporal_store(w, (GAS u32x2*)(d16 + 256 * j + 4 * lane));
;                     v[j] = (f32x4){bflo(w.x), bfhi(w.x), bflo(w.y), bfhi(w.y)}; }
;             } else { GAS float* dst = isx ? xdst + (size_t)row * 1024 : cdst + (size_t)(row - MX) * 1024;
; #pragma unroll
;                 for (int j = 0; j < 4; ++j) { v[j] += pw * gt[j] * ((y[j] * r) * gpo[j]); __builtin_nontemporal_store(v[j], (GAS f32x4*)(dst + 256 * j + 4 * lane)); } }
.LBB0_2444:
	v_lshlrev_b32_e32 v123, 16, v99
	v_lshlrev_b32_e32 v122, 16, v98
	v_and_b32_e32 v99, 0xffff0000, v99
	v_and_b32_e32 v98, 0xffff0000, v98
	v_pk_mul_f32 v[124:125], v[98:99], v[98:99]
	v_lshlrev_b32_e32 v127, 16, v91
	v_pk_fma_f32 v[124:125], v[122:123], v[122:123], v[124:125]
	v_lshlrev_b32_e32 v126, 16, v90
	v_and_b32_e32 v91, 0xffff0000, v91
	v_and_b32_e32 v90, 0xffff0000, v90
	v_pk_add_f32 v[124:125], v[124:125], v[124:125] op_sel_hi:[0,1]
	v_pk_mul_f32 v[128:129], v[90:91], v[90:91]
	v_lshlrev_b32_e32 v130, 16, v86
	v_and_b32_e32 v131, 0xffff0000, v86
	v_lshlrev_b32_e32 v86, 16, v87
	v_lshlrev_b32_e32 v132, 16, v84
	v_pk_fma_f32 v[128:129], v[126:127], v[126:127], v[128:129]
	v_mul_f32_e32 v133, v130, v130
	v_mul_f32_e32 v135, v131, v131
	v_and_b32_e32 v87, 0xffff0000, v87
	v_mul_f32_e32 v124, v86, v86
	v_mov_b32_e32 v134, v132
	v_pk_add_f32 v[128:129], v[128:129], v[128:129] op_sel_hi:[0,1]
	v_pk_fma_f32 v[136:137], v[86:87], v[86:87], v[124:125] op_sel_hi:[1,1,0]
	v_and_b32_e32 v121, 0xffff0000, v84
	v_lshlrev_b32_e32 v84, 16, v85
	v_and_b32_e32 v85, 0xffff0000, v85
	v_pk_add_f32 v[134:135], v[132:133], v[134:135]
	v_mul_f32_e32 v136, v121, v121
	v_mul_f32_e32 v128, v84, v84
	v_mul_f32_e32 v124, v85, v85
	v_mul_f32_e32 v138, v132, v132
	v_mov_b32_e32 v139, v135
	v_pk_add_f32 v[134:135], v[138:139], v[136:137]
	v_pk_add_f32 v[124:125], v[128:129], v[124:125]
	s_add_i32 s2, s19, 0xffff8000
	v_pk_add_f32 v[124:125], v[134:135], v[124:125]
	s_ashr_i32 s6, s19, 31
	v_add_f32_e32 v124, v124, v125
	s_nop 1
	v_add_f32_dpp v124, v124, v124 quad_perm:[1,0,3,2] row_mask:0xf bank_mask:0xf
	s_nop 1
	v_add_f32_dpp v124, v124, v124 quad_perm:[2,3,0,1] row_mask:0xf bank_mask:0xf
	s_nop 1
	v_add_f32_dpp v124, v124, v124 row_half_mirror row_mask:0xf bank_mask:0xf
	s_nop 1
	v_add_f32_dpp v124, v124, v124 row_mirror row_mask:0xf bank_mask:0xf
	s_nop 0
	v_readlane_b32 s64, v124, 0
	v_readlane_b32 s65, v124, 16
	v_readlane_b32 s66, v124, 32
	v_readlane_b32 s67, v124, 48
	v_mov_b32_e32 v125, s65
	v_add_f32_e32 v125, s64, v125
	v_mov_b32_e32 v124, s67
	v_add_f32_e32 v124, s66, v124
	v_add_f32_e32 v124, v125, v124
	s_waitcnt lgkmcnt(0)
	s_cmp_lt_i32 s19, 0x8000
	v_mov_b32_e32 v136, v123
	v_mov_b32_e32 v123, v98
	s_cselect_b32 s7, s6, 0
	s_cselect_b32 s6, s19, s2
	v_mov_b32_e32 v137, v99
	s_cselect_b32 s2, s75, s1
	s_cselect_b32 s8, s74, s0
	s_lshl_b64 s[6:7], s[6:7], 12
	s_waitcnt vmcnt(1)
	v_pk_mul_f32 v[134:135], v[50:51], 0.5 op_sel_hi:[1,0]
	s_add_u32 s6, s8, s6
	v_pk_mul_f32 v[128:129], v[52:53], 0.5 op_sel_hi:[1,0]
	s_addc_u32 s7, s2, s7
	v_mov_b32_e32 v133, v121
	s_add_i32 s14, s14, 8
	s_cmp_lt_i32 s14, s15
	v_fmamk_f32 v124, v124, 0x3a800000, v120
	v_mul_f32_e32 v125, 0x4b800000, v124
	v_cmp_gt_f32_e32 vcc, s18, v124
	s_nop 1
	v_cndmask_b32_e32 v124, v124, v125, vcc
	v_rsq_f32_e32 v124, v124
	s_nop 0
	v_mul_f32_e32 v125, 0x45800000, v124
	v_cndmask_b32_e32 v124, v124, v125, vcc
	v_pk_mul_f32 v[98:99], v[122:123], v[124:125] op_sel_hi:[1,0]
	v_pk_mul_f32 v[136:137], v[136:137], v[124:125] op_sel_hi:[1,0]
	v_pk_mul_f32 v[98:99], v[2:3], v[98:99]
	v_pk_mul_f32 v[122:123], v[4:5], v[136:137]
	v_pk_fma_f32 v[30:31], v[134:135], v[98:99], v[30:31]
	v_mov_b32_e32 v98, v127
	v_mov_b32_e32 v99, v91
	v_mov_b32_e32 v127, v90
	v_pk_fma_f32 v[32:33], v[128:129], v[122:123], v[32:33]
	v_pk_mul_f32 v[98:99], v[98:99], v[124:125] op_sel_hi:[1,0]
	v_pk_mul_f32 v[90:91], v[126:127], v[124:125] op_sel_hi:[1,0]
	global_store_dwordx4 v82, v[30:33], s[6:7] nt
	v_pk_mul_f32 v[90:91], v[6:7], v[90:91]
	v_pk_mul_f32 v[98:99], v[8:9], v[98:99]
	v_pk_mul_f32 v[30:31], v[56:57], 0.5 op_sel_hi:[1,0]
	v_pk_mul_f32 v[32:33], v[54:55], 0.5 op_sel_hi:[1,0]
	v_pk_fma_f32 v[28:29], v[30:31], v[98:99], v[28:29]
	v_pk_fma_f32 v[26:27], v[32:33], v[90:91], v[26:27]
	v_pk_mul_f32 v[30:31], v[86:87], v[124:125] op_sel_hi:[1,0]
	v_pk_mul_f32 v[32:33], v[130:131], v[124:125] op_sel_hi:[1,0]
	global_store_dwordx4 v82, v[26:29], s[6:7] offset:1024 nt
	v_pk_mul_f32 v[32:33], v[10:11], v[32:33]
	v_pk_mul_f32 v[30:31], v[12:13], v[30:31]
	v_pk_mul_f32 v[26:27], v[60:61], 0.5 op_sel_hi:[1,0]
	v_pk_mul_f32 v[28:29], v[58:59], 0.5 op_sel_hi:[1,0]
	v_pk_fma_f32 v[24:25], v[26:27], v[30:31], v[24:25]
	v_pk_fma_f32 v[22:23], v[28:29], v[32:33], v[22:23]
	v_pk_mul_f32 v[26:27], v[84:85], v[124:125] op_sel_hi:[1,0]
	v_pk_mul_f32 v[28:29], v[132:133], v[124:125] op_sel_hi:[1,0]
	global_store_dwordx4 v82, v[22:25], s[6:7] offset:2048 nt
	v_pk_mul_f32 v[28:29], v[14:15], v[28:29]
	v_pk_mul_f32 v[26:27], v[16:17], v[26:27]
	s_waitcnt vmcnt(3)
	v_pk_mul_f32 v[22:23], v[64:65], 0.5 op_sel_hi:[1,0]
	v_pk_mul_f32 v[24:25], v[62:63], 0.5 op_sel_hi:[1,0]
	v_pk_fma_f32 v[20:21], v[22:23], v[26:27], v[20:21]
	v_pk_fma_f32 v[18:19], v[24:25], v[28:29], v[18:19]
	global_store_dwordx4 v82, v[18:21], s[6:7] offset:3072 nt
	s_mov_b64 vcc, s[98:99]
	s_cbranch_vccz .Leload_skip_4
	s_waitcnt vmcnt(4)
	v_lshlrev_b32_e32 v66, 16, v68
	v_and_b32_e32 v67, 0xffff0000, v68
	v_lshlrev_b32_e32 v68, 16, v69
	v_and_b32_e32 v69, 0xffff0000, v69
	v_lshlrev_b32_e32 v70, 16, v72
	v_and_b32_e32 v71, 0xffff0000, v72
	v_lshlrev_b32_e32 v72, 16, v73
	v_and_b32_e32 v73, 0xffff0000, v73
	v_lshlrev_b32_e32 v74, 16, v76
	v_and_b32_e32 v75, 0xffff0000, v76
	v_lshlrev_b32_e32 v76, 16, v77
	v_and_b32_e32 v77, 0xffff0000, v77
	v_lshlrev_b32_e32 v78, 16, v80
	v_and_b32_e32 v79, 0xffff0000, v80
	v_lshlrev_b32_e32 v80, 16, v81
	v_and_b32_e32 v81, 0xffff0000, v81

; __global__ void __launch_bounds__(512, 2) fwd_kernel(Args a) {
;     extern __shared__ __attribute__((aligned(16))) unsigned char lds_raw[];
	.amdhsa_kernel _Z10fwd_kernel4Args
		.amdhsa_group_segment_fixed_size 0
		.amdhsa_private_segment_fixed_size 0
		.amdhsa_kernarg_size 448
		.amdhsa_user_sgpr_count 2
		.amdhsa_user_sgpr_dispatch_ptr 0
		.amdhsa_user_sgpr_queue_ptr 0
		.amdhsa_user_sgpr_kernarg_segment_ptr 1
		.amdhsa_user_sgpr_dispatch_id 0
		.amdhsa_user_sgpr_kernarg_preload_length 0
		.amdhsa_user_sgpr_kernarg_preload_offset 0
		.amdhsa_user_sgpr_private_segment_size 0
		.amdhsa_uses_dynamic_stack 0
		.amdhsa_enable_private_segment 0
		.amdhsa_system_sgpr_workgroup_id_x 1
		.amdhsa_system_sgpr_workgroup_id_y 0
		.amdhsa_system_sgpr_workgroup_id_z 0
		.amdhsa_system_sgpr_workgroup_info 0
		.amdhsa_system_vgpr_workitem_id 2
		.amdhsa_next_free_vgpr 256
		.amdhsa_next_free_sgpr 100
		.amdhsa_accum_offset 256
		.amdhsa_reserve_vcc 1
		.amdhsa_float_round_mode_32 0
		.amdhsa_float_round_mode_16_64 0
		.amdhsa_float_denorm_mode_32 3
		.amdhsa_float_denorm_mode_16_64 3
		.amdhsa_dx10_clamp 1
		.amdhsa_ieee_mode 1
		.amdhsa_fp16_overflow 0
		.amdhsa_tg_split 0
		.amdhsa_exception_fp_ieee_invalid_op 0
		.amdhsa_exception_fp_denorm_src 0
		.amdhsa_exception_fp_ieee_div_zero 0
		.amdhsa_exception_fp_ieee_overflow 0
		.amdhsa_exception_fp_ieee_underflow 0
		.amdhsa_exception_fp_ieee_inexact 0
		.amdhsa_exception_int_div_zero 0
	.end_amdhsa_kernel

; __global__ void __launch_bounds__(512, 2) fwd_kernel(Args a) {
;     extern __shared__ __attribute__((aligned(16))) unsigned char lds_raw[];
amdhsa.kernels:
  - .agpr_count:     0
    .args:
      - .offset:         0
        .size:           192
        .value_kind:     by_value
      - .offset:         192
        .size:           4
        .value_kind:     hidden_block_count_x
      - .offset:         196
        .size:           4
        .value_kind:     hidden_block_count_y
      - .offset:         200
        .size:           4
        .value_kind:     hidden_block_count_z
      - .offset:         204
        .size:           2
        .value_kind:     hidden_group_size_x
      - .offset:         206
        .size:           2
        .value_kind:     hidden_group_size_y
      - .offset:         208
        .size:           2
        .value_kind:     hidden_group_size_z
      - .offset:         210
        .size:           2
        .value_kind:     hidden_remainder_x
      - .offset:         212
        .size:           2
        .value_kind:     hidden_remainder_y
      - .offset:         214
        .size:           2
        .value_kind:     hidden_remainder_z
      - .offset:         232
        .size:           8
        .value_kind:     hidden_global_offset_x
      - .offset:         240
        .size:           8
        .value_kind:     hidden_global_offset_y
      - .offset:         248
        .size:           8
        .value_kind:     hidden_global_offset_z
      - .offset:         256
        .size:           2
        .value_kind:     hidden_grid_dims
      - .offset:         280
        .size:           8
        .value_kind:     hidden_multigrid_sync_arg
      - .offset:         312
        .size:           4
        .value_kind:     hidden_dynamic_lds_size
    .group_segment_fixed_size: 0
    .kernarg_segment_align: 8
    .kernarg_segment_size: 448
    .language:       OpenCL C
    .language_version:
      - 2
      - 0
    .max_flat_workgroup_size: 512
    .name:           _Z10fwd_kernel4Args
    .private_segment_fixed_size: 0
    .sgpr_count:     106
    .sgpr_spill_count: 40
    .symbol:         _Z10fwd_kernel4Args.kd
    .uniform_work_group_size: 1
    .uses_dynamic_stack: false
    .vgpr_count:     256
    .vgpr_spill_count: 0
    .wavefront_size: 64
